# MFMA order zz_m: accumulate chains with alternating K order so the A fragment (srcB) repeats across chain boundaries
# baseline (speedup 1.0000x reference)
; #define PG8_STAGE(bufoff, gbase, voff) do { _Pragma("unroll") for (int _i = 0; _i < 2; ++_i) \
;         __builtin_amdgcn_global_load_lds((const unsigned*)((const char*)(gbase) + (voff)[_i]), (PG8_LAS unsigned*)(lds + (bufoff) + ldsw + _i * 8192), 16, 0, 0); } while (0)
; #define PG8_LDA(dst, b, h) do { _Pragma("unroll") for (int m = 0; m < 4; ++m) _Pragma("unroll") for (int k = 0; k < 2; ++k) dst[m][k] = *(const PG8_LAS bf16x8*)(lds + PG8_SA(b, h) + aoff + m * 2048 + k * 1024); } while (0)
; #define PG8_LDB(dst, b, h) do { _Pragma("unroll") for (int n = 0; n < 2; ++n) _Pragma("unroll") for (int k = 0; k < 2; ++k) dst[n][k] = *(const PG8_LAS bf16x8*)(lds + PG8_SB(b, h) + boff + n * 2048 + k * 1024); } while (0)
; template <class Epi, class Sched, bool ALIGN_EPI = false, bool SP2 = false>
; __device__ __forceinline__ void gemm_phase(PG8_LAS unsigned char* lds, const Gemm g, const Sched& S, const Epi& E) {
;     ...
;         for (int t = 0; t < nt; t += 2) {
;             const bool last = (t == nt - 2);
;             const char* a1 = cA + (size_t)(t + 1) * kstep;
;             const char* a2 = last ? nA : cA + (size_t)(t + 2) * kstep; const char* b2 = last ? nB : cB + (size_t)(t + 2) * kstep;
;             const char* a3 = a2 + kstep; const char* b3 = b2 + kstep;
;             if (last && has_next) S.a_ready(nxt);
;             if constexpr (SP2) {
;             PG8_LDB(B0, 0, 0); PG8_LDB(B1, 0, 1); PG8_SCHED; PG8_LDA(At, 0, 0); PG8_STAGE(PG8_SA(1, 1), a1 + hstep, voffA);
;             PG8_WAIT_V(8); PG8_WAIT_L(0); PG8_BAR; PG8_MMA(0, 0, At, B0); PG8_MMA(0, 1, At, B1); PG8_BAR; PG8_SCHED;
;             PG8_LDA(At, 0, 1); PG8_STAGE(PG8_SB(0, 0), b2, voffB); PG8_STAGE(PG8_SB(0, 1), b2 + hstep, voffB); PG8_STAGE(PG8_SA(0, 0), a2, voffA);
;             PG8_WAIT_V(8); PG8_WAIT_L(0); PG8_BAR; PG8_MMA(1, 0, At, B0); PG8_MMA(1, 1, At, B1); PG8_BAR; PG8_SCHED;
;             PG8_LDB(B0, 1, 0); PG8_LDB(B1, 1, 1); PG8_SCHED; PG8_LDA(At, 1, 0); PG8_STAGE(PG8_SA(0, 1), a2 + hstep, voffA);
;             PG8_WAIT_V(8); PG8_WAIT_L(0); PG8_BAR; PG8_MMA(0, 0, At, B0); PG8_MMA(0, 1, At, B1); PG8_BAR; PG8_SCHED;
;             PG8_LDA(At, 1, 1); PG8_STAGE(PG8_SB(1, 0), b3, voffB); PG8_STAGE(PG8_SB(1, 1), b3 + hstep, voffB); PG8_STAGE(PG8_SA(1, 0), a3, voffA);
;             PG8_WAIT_V(8); PG8_WAIT_L(0); PG8_BAR; PG8_MMA(1, 0, At, B0); PG8_MMA(1, 1, At, B1); PG8_BAR; PG8_SCHED;
.LBB11_228:
	ds_read_b128 v[152:155], v149
	ds_read_b128 v[156:159], v149 offset:1024
	ds_read_b128 v[160:163], v149 offset:2048
	ds_read_b128 v[164:167], v149 offset:3072
	ds_read_b128 v[168:171], v150
	ds_read_b128 v[172:175], v150 offset:1024
	ds_read_b128 v[176:179], v150 offset:2048
	ds_read_b128 v[180:183], v150 offset:3072
	s_add_u32 s30, s28, 0xfff80080
	s_addc_u32 s31, s29, -1
	s_cmp_eq_u32 s61, 28
	s_cselect_b32 s35, s21, s31
	s_cselect_b32 s34, s57, s30
	s_cselect_b32 s31, s19, s60
	s_cselect_b32 s30, s58, s59
	v_lshl_add_u64 v[144:145], s[28:29], 0, v[140:141]
	s_add_i32 m0, s27, 0xc000
	ds_read_b128 v[184:187], v151
	ds_read_b128 v[188:191], v151 offset:1024
	ds_read_b128 v[192:195], v151 offset:2048
	ds_read_b128 v[196:199], v151 offset:3072
	ds_read_b128 v[200:203], v151 offset:4096
	ds_read_b128 v[204:207], v151 offset:5120
	ds_read_b128 v[210:213], v151 offset:6144
	ds_read_b128 v[214:217], v151 offset:7168
	global_load_lds_dwordx4 v[144:145], off
	v_lshl_add_u64 v[144:145], s[28:29], 0, v[142:143]
	s_add_i32 m0, s27, 0xe000
	s_nop 0
	global_load_lds_dwordx4 v[144:145], off
	s_waitcnt vmcnt(8)
	s_waitcnt lgkmcnt(0)
	s_barrier
	s_setprio 1
	s_waitcnt lgkmcnt(0)
	v_mfma_f32_16x16x32_bf16 v[126:129], v[152:155], v[184:187], v[126:129]
	v_mfma_f32_16x16x32_bf16 v[126:129], v[156:159], v[188:191], v[126:129]
	v_mfma_f32_16x16x32_bf16 v[122:125], v[164:167], v[188:191], v[122:125]
	v_mfma_f32_16x16x32_bf16 v[122:125], v[160:163], v[184:187], v[122:125]
	v_mfma_f32_16x16x32_bf16 v[118:121], v[152:155], v[192:195], v[118:121]
	v_mfma_f32_16x16x32_bf16 v[118:121], v[156:159], v[196:199], v[118:121]
	v_mfma_f32_16x16x32_bf16 v[110:113], v[164:167], v[196:199], v[110:113]
	v_mfma_f32_16x16x32_bf16 v[110:113], v[160:163], v[192:195], v[110:113]
	v_mfma_f32_16x16x32_bf16 v[102:105], v[152:155], v[200:203], v[102:105]
	v_mfma_f32_16x16x32_bf16 v[102:105], v[156:159], v[204:207], v[102:105]
	v_mfma_f32_16x16x32_bf16 v[94:97], v[164:167], v[204:207], v[94:97]
	v_mfma_f32_16x16x32_bf16 v[94:97], v[160:163], v[200:203], v[94:97]
	v_mfma_f32_16x16x32_bf16 v[86:89], v[152:155], v[210:213], v[86:89]
	v_mfma_f32_16x16x32_bf16 v[86:89], v[156:159], v[214:217], v[86:89]
	v_mfma_f32_16x16x32_bf16 v[78:81], v[164:167], v[214:217], v[78:81]
	v_mfma_f32_16x16x32_bf16 v[78:81], v[160:163], v[210:213], v[78:81]
	s_setprio 0
	s_setprio 1
	v_mfma_f32_16x16x32_bf16 v[114:117], v[168:171], v[184:187], v[114:117]
	v_mfma_f32_16x16x32_bf16 v[114:117], v[172:175], v[188:191], v[114:117]
	v_mfma_f32_16x16x32_bf16 v[106:109], v[180:183], v[188:191], v[106:109]
	v_mfma_f32_16x16x32_bf16 v[106:109], v[176:179], v[184:187], v[106:109]
	v_mfma_f32_16x16x32_bf16 v[98:101], v[168:171], v[192:195], v[98:101]
	v_mfma_f32_16x16x32_bf16 v[98:101], v[172:175], v[196:199], v[98:101]
	v_mfma_f32_16x16x32_bf16 v[90:93], v[180:183], v[196:199], v[90:93]
	v_mfma_f32_16x16x32_bf16 v[90:93], v[176:179], v[192:195], v[90:93]
	v_mfma_f32_16x16x32_bf16 v[82:85], v[168:171], v[200:203], v[82:85]
	v_mfma_f32_16x16x32_bf16 v[82:85], v[172:175], v[204:207], v[82:85]
	v_mfma_f32_16x16x32_bf16 v[74:77], v[180:183], v[204:207], v[74:77]
	v_mfma_f32_16x16x32_bf16 v[74:77], v[176:179], v[200:203], v[74:77]
	v_mfma_f32_16x16x32_bf16 v[70:73], v[168:171], v[210:213], v[70:73]
	v_mfma_f32_16x16x32_bf16 v[70:73], v[172:175], v[214:217], v[70:73]
	v_mfma_f32_16x16x32_bf16 v[66:69], v[180:183], v[214:217], v[66:69]
	v_mfma_f32_16x16x32_bf16 v[66:69], v[176:179], v[210:213], v[66:69]
	s_setprio 0
	s_barrier
	s_add_i32 s62, s50, s37
	v_lshl_add_u64 v[144:145], s[30:31], 0, v[134:135]
	s_mov_b32 m0, s62
	ds_read_b128 v[184:187], v151 offset:16384
	ds_read_b128 v[188:191], v151 offset:17408
	ds_read_b128 v[192:195], v151 offset:18432
	ds_read_b128 v[196:199], v151 offset:19456
	ds_read_b128 v[200:203], v151 offset:20480
	ds_read_b128 v[204:207], v151 offset:21504
	ds_read_b128 v[210:213], v151 offset:22528
	ds_read_b128 v[214:217], v151 offset:23552
	global_load_lds_dwordx4 v[144:145], off
	s_add_i32 m0, s62, 0x2000
	s_add_u32 s62, s30, 0x80000
	v_lshl_add_u64 v[218:219], s[30:31], 0, v[130:131]
	s_addc_u32 s63, s31, 0
	s_add_i32 s64, s51, s37
	global_load_lds_dwordx4 v[218:219], off
	v_lshl_add_u64 v[220:221], s[62:63], 0, v[134:135]
	s_mov_b32 m0, s64
	v_lshl_add_u64 v[222:223], s[34:35], 0, v[132:133]
	global_load_lds_dwordx4 v[220:221], off
	v_lshl_add_u64 v[220:221], s[62:63], 0, v[130:131]
	s_add_i32 m0, s64, 0x2000
	s_nop 0
	global_load_lds_dwordx4 v[220:221], off
	v_lshl_add_u64 v[220:221], s[34:35], 0, v[136:137]
	s_mov_b32 m0, s27
	s_nop 0
	global_load_lds_dwordx4 v[220:221], off
	s_mov_b32 m0, s39
	s_nop 0
	global_load_lds_dwordx4 v[222:223], off
	s_waitcnt vmcnt(8)
	s_waitcnt lgkmcnt(0)
	s_barrier
; #define PG8_STAGE(bufoff, gbase, voff) do { _Pragma("unroll") for (int _i = 0; _i < 2; ++_i) \
;         __builtin_amdgcn_global_load_lds((const unsigned*)((const char*)(gbase) + (voff)[_i]), (PG8_LAS unsigned*)(lds + (bufoff) + ldsw + _i * 8192), 16, 0, 0); } while (0)
; #define PG8_LDA(dst, b, h) do { _Pragma("unroll") for (int m = 0; m < 4; ++m) _Pragma("unroll") for (int k = 0; k < 2; ++k) dst[m][k] = *(const PG8_LAS bf16x8*)(lds + PG8_SA(b, h) + aoff + m * 2048 + k * 1024); } while (0)
; #define PG8_LDB(dst, b, h) do { _Pragma("unroll") for (int n = 0; n < 2; ++n) _Pragma("unroll") for (int k = 0; k < 2; ++k) dst[n][k] = *(const PG8_LAS bf16x8*)(lds + PG8_SB(b, h) + boff + n * 2048 + k * 1024); } while (0)
; #define PG8_MMA(ai, bj, At, Bt) do { __builtin_amdgcn_s_setprio(1); _Pragma("unroll") for (int m = 0; m < 4; ++m) _Pragma("unroll") for (int n = 0; n < 2; ++n) _Pragma("unroll") for (int k = 0; k < 2; ++k) \
;         acc[ai][bj][m][n] = __builtin_amdgcn_mfma_f32_16x16x32_bf16(Bt[n][k], At[m][k], acc[ai][bj][m][n], 0, 0, 0); __builtin_amdgcn_s_setprio(0); } while (0)
; #define PG8_WAIT_V(n) asm volatile("s_waitcnt vmcnt(" #n ")" ::: "memory")
; #define PG8_WAIT_L(n) asm volatile("s_waitcnt lgkmcnt(" #n ")" ::: "memory")
; #define PG8_BAR __builtin_amdgcn_s_barrier()
; #define PG8_SCHED __builtin_amdgcn_sched_barrier(0)
; template <class Epi, class Sched, bool ALIGN_EPI = false, bool SP2 = false>
; __device__ __forceinline__ void gemm_phase(PG8_LAS unsigned char* lds, const Gemm g, const Sched& S, const Epi& E) {
;     ...
;             PG8_LDB(B0, 0, 0); PG8_LDB(B1, 0, 1); PG8_SCHED; PG8_LDA(At, 0, 0); PG8_STAGE(PG8_SA(1, 1), a1 + hstep, voffA);
;             PG8_WAIT_V(8); PG8_WAIT_L(0); PG8_BAR; PG8_MMA(0, 0, At, B0); PG8_MMA(0, 1, At, B1); PG8_BAR; PG8_SCHED;
;             PG8_LDA(At, 0, 1); PG8_STAGE(PG8_SB(0, 0), b2, voffB); PG8_STAGE(PG8_SB(0, 1), b2 + hstep, voffB); PG8_STAGE(PG8_SA(0, 0), a2, voffA);
;             PG8_WAIT_V(8); PG8_WAIT_L(0); PG8_BAR; PG8_MMA(1, 0, At, B0); PG8_MMA(1, 1, At, B1); PG8_BAR; PG8_SCHED;
;             PG8_LDB(B0, 1, 0); PG8_LDB(B1, 1, 1); PG8_SCHED; PG8_LDA(At, 1, 0); PG8_STAGE(PG8_SA(0, 1), a2 + hstep, voffA);
;             PG8_WAIT_V(8); PG8_WAIT_L(0); PG8_BAR; PG8_MMA(0, 0, At, B0); PG8_MMA(0, 1, At, B1); PG8_BAR; PG8_SCHED;
	s_setprio 1
	s_waitcnt lgkmcnt(0)
	v_mfma_f32_16x16x32_bf16 v[62:65], v[152:155], v[184:187], v[62:65]
	v_mfma_f32_16x16x32_bf16 v[62:65], v[156:159], v[188:191], v[62:65]
	v_mfma_f32_16x16x32_bf16 v[58:61], v[164:167], v[188:191], v[58:61]
	v_mfma_f32_16x16x32_bf16 v[58:61], v[160:163], v[184:187], v[58:61]
	v_mfma_f32_16x16x32_bf16 v[54:57], v[152:155], v[192:195], v[54:57]
	v_mfma_f32_16x16x32_bf16 v[54:57], v[156:159], v[196:199], v[54:57]
	v_mfma_f32_16x16x32_bf16 v[46:49], v[164:167], v[196:199], v[46:49]
	v_mfma_f32_16x16x32_bf16 v[46:49], v[160:163], v[192:195], v[46:49]
	v_mfma_f32_16x16x32_bf16 v[38:41], v[152:155], v[200:203], v[38:41]
	v_mfma_f32_16x16x32_bf16 v[38:41], v[156:159], v[204:207], v[38:41]
	v_mfma_f32_16x16x32_bf16 v[30:33], v[164:167], v[204:207], v[30:33]
	v_mfma_f32_16x16x32_bf16 v[30:33], v[160:163], v[200:203], v[30:33]
	v_mfma_f32_16x16x32_bf16 v[22:25], v[152:155], v[210:213], v[22:25]
	v_mfma_f32_16x16x32_bf16 v[22:25], v[156:159], v[214:217], v[22:25]
	v_mfma_f32_16x16x32_bf16 v[14:17], v[164:167], v[214:217], v[14:17]
	v_mfma_f32_16x16x32_bf16 v[14:17], v[160:163], v[210:213], v[14:17]
	s_setprio 0
	s_setprio 1
	v_mfma_f32_16x16x32_bf16 v[50:53], v[168:171], v[184:187], v[50:53]
	v_mfma_f32_16x16x32_bf16 v[50:53], v[172:175], v[188:191], v[50:53]
	v_mfma_f32_16x16x32_bf16 v[42:45], v[180:183], v[188:191], v[42:45]
	v_mfma_f32_16x16x32_bf16 v[42:45], v[176:179], v[184:187], v[42:45]
	v_mfma_f32_16x16x32_bf16 v[34:37], v[168:171], v[192:195], v[34:37]
	v_mfma_f32_16x16x32_bf16 v[34:37], v[172:175], v[196:199], v[34:37]
	v_mfma_f32_16x16x32_bf16 v[26:29], v[180:183], v[196:199], v[26:29]
	v_mfma_f32_16x16x32_bf16 v[26:29], v[176:179], v[192:195], v[26:29]
	v_mfma_f32_16x16x32_bf16 v[18:21], v[168:171], v[200:203], v[18:21]
	v_mfma_f32_16x16x32_bf16 v[18:21], v[172:175], v[204:207], v[18:21]
	v_mfma_f32_16x16x32_bf16 v[10:13], v[180:183], v[204:207], v[10:13]
	v_mfma_f32_16x16x32_bf16 v[10:13], v[176:179], v[200:203], v[10:13]
	v_mfma_f32_16x16x32_bf16 v[6:9], v[168:171], v[210:213], v[6:9]
	v_mfma_f32_16x16x32_bf16 v[6:9], v[172:175], v[214:217], v[6:9]
	v_mfma_f32_16x16x32_bf16 v[2:5], v[180:183], v[214:217], v[2:5]
	v_mfma_f32_16x16x32_bf16 v[2:5], v[176:179], v[210:213], v[2:5]
	s_setprio 0
	s_barrier
	s_add_i32 s62, 0, 0x18000
	s_add_i32 s63, 0, 0x1c000
	v_add_u32_e32 v164, s62, v147
	v_add_u32_e32 v180, s63, v147
	ds_read_b128 v[152:155], v164
	ds_read_b128 v[156:159], v164 offset:1024
	ds_read_b128 v[160:163], v164 offset:2048
	ds_read_b128 v[164:167], v164 offset:3072
	ds_read_b128 v[168:171], v180
	ds_read_b128 v[172:175], v180 offset:1024
	ds_read_b128 v[176:179], v180 offset:2048
	ds_read_b128 v[180:183], v180 offset:3072
	s_add_u32 s34, s34, 0x80000
	s_addc_u32 s35, s35, 0
	s_mov_b32 m0, s40
	v_lshl_add_u64 v[224:225], s[34:35], 0, v[136:137]
	ds_read_b128 v[184:187], v151 offset:32768
	ds_read_b128 v[188:191], v151 offset:33792
	ds_read_b128 v[192:195], v151 offset:34816
	ds_read_b128 v[196:199], v151 offset:35840
	ds_read_b128 v[200:203], v151 offset:36864
	ds_read_b128 v[204:207], v151 offset:37888
	ds_read_b128 v[210:213], v151 offset:38912
	ds_read_b128 v[214:217], v151 offset:39936
	global_load_lds_dwordx4 v[224:225], off
	v_lshl_add_u64 v[224:225], s[34:35], 0, v[132:133]
	s_mov_b32 m0, s41
	s_nop 0
	global_load_lds_dwordx4 v[224:225], off
	s_waitcnt vmcnt(8)
	s_waitcnt lgkmcnt(0)
	s_barrier
	s_setprio 1
	s_waitcnt lgkmcnt(0)
	v_mfma_f32_16x16x32_bf16 v[126:129], v[152:155], v[184:187], v[126:129]
	v_mfma_f32_16x16x32_bf16 v[126:129], v[156:159], v[188:191], v[126:129]
	v_mfma_f32_16x16x32_bf16 v[122:125], v[164:167], v[188:191], v[122:125]
	v_mfma_f32_16x16x32_bf16 v[122:125], v[160:163], v[184:187], v[122:125]
	v_mfma_f32_16x16x32_bf16 v[118:121], v[152:155], v[192:195], v[118:121]
	v_mfma_f32_16x16x32_bf16 v[118:121], v[156:159], v[196:199], v[118:121]
	v_mfma_f32_16x16x32_bf16 v[110:113], v[164:167], v[196:199], v[110:113]
	v_mfma_f32_16x16x32_bf16 v[110:113], v[160:163], v[192:195], v[110:113]
	v_mfma_f32_16x16x32_bf16 v[102:105], v[152:155], v[200:203], v[102:105]
	v_mfma_f32_16x16x32_bf16 v[102:105], v[156:159], v[204:207], v[102:105]
	v_mfma_f32_16x16x32_bf16 v[94:97], v[164:167], v[204:207], v[94:97]
	v_mfma_f32_16x16x32_bf16 v[94:97], v[160:163], v[200:203], v[94:97]
	v_mfma_f32_16x16x32_bf16 v[86:89], v[152:155], v[210:213], v[86:89]
	v_mfma_f32_16x16x32_bf16 v[86:89], v[156:159], v[214:217], v[86:89]
	v_mfma_f32_16x16x32_bf16 v[78:81], v[164:167], v[214:217], v[78:81]
	v_mfma_f32_16x16x32_bf16 v[78:81], v[160:163], v[210:213], v[78:81]
	s_setprio 0
	s_setprio 1
	v_mfma_f32_16x16x32_bf16 v[114:117], v[168:171], v[184:187], v[114:117]
	v_mfma_f32_16x16x32_bf16 v[114:117], v[172:175], v[188:191], v[114:117]
	v_mfma_f32_16x16x32_bf16 v[106:109], v[180:183], v[188:191], v[106:109]
	v_mfma_f32_16x16x32_bf16 v[106:109], v[176:179], v[184:187], v[106:109]
	v_mfma_f32_16x16x32_bf16 v[98:101], v[168:171], v[192:195], v[98:101]
	v_mfma_f32_16x16x32_bf16 v[98:101], v[172:175], v[196:199], v[98:101]
	v_mfma_f32_16x16x32_bf16 v[90:93], v[180:183], v[196:199], v[90:93]
	v_mfma_f32_16x16x32_bf16 v[90:93], v[176:179], v[192:195], v[90:93]
	v_mfma_f32_16x16x32_bf16 v[82:85], v[168:171], v[200:203], v[82:85]
	v_mfma_f32_16x16x32_bf16 v[82:85], v[172:175], v[204:207], v[82:85]
	v_mfma_f32_16x16x32_bf16 v[74:77], v[180:183], v[204:207], v[74:77]
	v_mfma_f32_16x16x32_bf16 v[74:77], v[176:179], v[200:203], v[74:77]
	v_mfma_f32_16x16x32_bf16 v[70:73], v[168:171], v[210:213], v[70:73]
	v_mfma_f32_16x16x32_bf16 v[70:73], v[172:175], v[214:217], v[70:73]
	v_mfma_f32_16x16x32_bf16 v[66:69], v[180:183], v[214:217], v[66:69]
	v_mfma_f32_16x16x32_bf16 v[66:69], v[176:179], v[210:213], v[66:69]
	s_setprio 0
	s_barrier
; #define PG8_STAGE(bufoff, gbase, voff) do { _Pragma("unroll") for (int _i = 0; _i < 2; ++_i) \
;         __builtin_amdgcn_global_load_lds((const unsigned*)((const char*)(gbase) + (voff)[_i]), (PG8_LAS unsigned*)(lds + (bufoff) + ldsw + _i * 8192), 16, 0, 0); } while (0)
; #define PG8_LDA(dst, b, h) do { _Pragma("unroll") for (int m = 0; m < 4; ++m) _Pragma("unroll") for (int k = 0; k < 2; ++k) dst[m][k] = *(const PG8_LAS bf16x8*)(lds + PG8_SA(b, h) + aoff + m * 2048 + k * 1024); } while (0)
; #define PG8_MMA(ai, bj, At, Bt) do { __builtin_amdgcn_s_setprio(1); _Pragma("unroll") for (int m = 0; m < 4; ++m) _Pragma("unroll") for (int n = 0; n < 2; ++n) _Pragma("unroll") for (int k = 0; k < 2; ++k) \
;         acc[ai][bj][m][n] = __builtin_amdgcn_mfma_f32_16x16x32_bf16(Bt[n][k], At[m][k], acc[ai][bj][m][n], 0, 0, 0); __builtin_amdgcn_s_setprio(0); } while (0)
; #define PG8_WAIT_V(n) asm volatile("s_waitcnt vmcnt(" #n ")" ::: "memory")
; #define PG8_WAIT_L(n) asm volatile("s_waitcnt lgkmcnt(" #n ")" ::: "memory")
; #define PG8_BAR __builtin_amdgcn_s_barrier()
; #define PG8_SCHED __builtin_amdgcn_sched_barrier(0)
; template <class Epi, class Sched, bool ALIGN_EPI = false, bool SP2 = false>
; __device__ __forceinline__ void gemm_phase(PG8_LAS unsigned char* lds, const Gemm g, const Sched& S, const Epi& E) {
;     ...
;             PG8_WAIT_V(8); PG8_WAIT_L(0); PG8_BAR; PG8_MMA(0, 0, At, B0); PG8_MMA(0, 1, At, B1); PG8_BAR; PG8_SCHED;
;             PG8_LDA(At, 1, 1); PG8_STAGE(PG8_SB(1, 0), b3, voffB); PG8_STAGE(PG8_SB(1, 1), b3 + hstep, voffB); PG8_STAGE(PG8_SA(1, 0), a3, voffA);
;             PG8_WAIT_V(8); PG8_WAIT_L(0); PG8_BAR; PG8_MMA(1, 0, At, B0); PG8_MMA(1, 1, At, B1); PG8_BAR; PG8_SCHED;
	s_add_i32 s34, s62, s37
	v_lshl_add_u64 v[144:145], v[144:145], 0, s[6:7]
	s_mov_b32 m0, s34
	ds_read_b128 v[184:187], v151 offset:49152
	ds_read_b128 v[188:191], v151 offset:50176
	ds_read_b128 v[192:195], v151 offset:51200
	ds_read_b128 v[196:199], v151 offset:52224
	ds_read_b128 v[200:203], v151 offset:53248
	ds_read_b128 v[204:207], v151 offset:54272
	ds_read_b128 v[210:213], v151 offset:55296
	ds_read_b128 v[214:217], v151 offset:56320
	global_load_lds_dwordx4 v[144:145], off
	s_add_i32 m0, s34, 0x2000
	s_add_u32 s30, s30, 0x80080
	v_lshl_add_u64 v[144:145], v[218:219], 0, s[6:7]
	s_addc_u32 s31, s31, 0
	s_add_i32 s34, s63, s37
	global_load_lds_dwordx4 v[144:145], off
	v_lshl_add_u64 v[144:145], s[30:31], 0, v[134:135]
	s_mov_b32 m0, s34
	s_nop 0
	global_load_lds_dwordx4 v[144:145], off
	v_lshl_add_u64 v[144:145], s[30:31], 0, v[130:131]
	s_add_i32 m0, s34, 0x2000
	s_nop 0
	global_load_lds_dwordx4 v[144:145], off
	v_lshl_add_u64 v[144:145], v[220:221], 0, s[6:7]
	s_mov_b32 m0, s48
	s_nop 0
	global_load_lds_dwordx4 v[144:145], off
	v_lshl_add_u64 v[144:145], v[222:223], 0, s[6:7]
	s_mov_b32 m0, s49
	s_nop 0
	global_load_lds_dwordx4 v[144:145], off
	s_waitcnt vmcnt(8)
	s_waitcnt lgkmcnt(0)
	s_barrier
	s_setprio 1
	s_waitcnt lgkmcnt(0)
	v_mfma_f32_16x16x32_bf16 v[62:65], v[152:155], v[184:187], v[62:65]
	v_mfma_f32_16x16x32_bf16 v[62:65], v[156:159], v[188:191], v[62:65]
	v_mfma_f32_16x16x32_bf16 v[58:61], v[164:167], v[188:191], v[58:61]
	v_mfma_f32_16x16x32_bf16 v[58:61], v[160:163], v[184:187], v[58:61]
	v_mfma_f32_16x16x32_bf16 v[54:57], v[152:155], v[192:195], v[54:57]
	v_mfma_f32_16x16x32_bf16 v[54:57], v[156:159], v[196:199], v[54:57]
	v_mfma_f32_16x16x32_bf16 v[46:49], v[164:167], v[196:199], v[46:49]
	v_mfma_f32_16x16x32_bf16 v[46:49], v[160:163], v[192:195], v[46:49]
	v_mfma_f32_16x16x32_bf16 v[38:41], v[152:155], v[200:203], v[38:41]
	v_mfma_f32_16x16x32_bf16 v[38:41], v[156:159], v[204:207], v[38:41]
	v_mfma_f32_16x16x32_bf16 v[30:33], v[164:167], v[204:207], v[30:33]
	v_mfma_f32_16x16x32_bf16 v[30:33], v[160:163], v[200:203], v[30:33]
	v_mfma_f32_16x16x32_bf16 v[22:25], v[152:155], v[210:213], v[22:25]
	v_mfma_f32_16x16x32_bf16 v[22:25], v[156:159], v[214:217], v[22:25]
	v_mfma_f32_16x16x32_bf16 v[14:17], v[164:167], v[214:217], v[14:17]
	v_mfma_f32_16x16x32_bf16 v[14:17], v[160:163], v[210:213], v[14:17]
	s_setprio 0
	s_setprio 1
	v_mfma_f32_16x16x32_bf16 v[50:53], v[168:171], v[184:187], v[50:53]
	v_mfma_f32_16x16x32_bf16 v[50:53], v[172:175], v[188:191], v[50:53]
	v_mfma_f32_16x16x32_bf16 v[42:45], v[180:183], v[188:191], v[42:45]
	v_mfma_f32_16x16x32_bf16 v[42:45], v[176:179], v[184:187], v[42:45]
	v_mfma_f32_16x16x32_bf16 v[34:37], v[168:171], v[192:195], v[34:37]
	v_mfma_f32_16x16x32_bf16 v[34:37], v[172:175], v[196:199], v[34:37]
	v_mfma_f32_16x16x32_bf16 v[26:29], v[180:183], v[196:199], v[26:29]
	v_mfma_f32_16x16x32_bf16 v[26:29], v[176:179], v[192:195], v[26:29]
	v_mfma_f32_16x16x32_bf16 v[18:21], v[168:171], v[200:203], v[18:21]
	v_mfma_f32_16x16x32_bf16 v[18:21], v[172:175], v[204:207], v[18:21]
	v_mfma_f32_16x16x32_bf16 v[10:13], v[180:183], v[204:207], v[10:13]
	v_mfma_f32_16x16x32_bf16 v[10:13], v[176:179], v[200:203], v[10:13]
	v_mfma_f32_16x16x32_bf16 v[6:9], v[168:171], v[210:213], v[6:9]
	v_mfma_f32_16x16x32_bf16 v[6:9], v[172:175], v[214:217], v[6:9]
	v_mfma_f32_16x16x32_bf16 v[2:5], v[180:183], v[214:217], v[2:5]
	v_mfma_f32_16x16x32_bf16 v[2:5], v[176:179], v[210:213], v[2:5]
	s_setprio 0
	s_barrier
	s_add_i32 s61, s61, 2
	s_add_u32 s28, s28, 0x100
	s_addc_u32 s29, s29, 0
	s_add_u32 s59, s59, 0x100
	s_addc_u32 s60, s60, 0
	s_cmp_gt_u32 s61, 29
	s_cbranch_scc0 .LBB11_228
	s_and_b64 vcc, exec, s[8:9]
	s_cbranch_vccz .LBB11_231
	s_barrier

; #define PG8_STAGE(bufoff, gbase, voff) do { _Pragma("unroll") for (int _i = 0; _i < 2; ++_i) \
;         __builtin_amdgcn_global_load_lds((const unsigned*)((const char*)(gbase) + (voff)[_i]), (PG8_LAS unsigned*)(lds + (bufoff) + ldsw + _i * 8192), 16, 0, 0); } while (0)
; #define PG8_LDA(dst, b, h) do { _Pragma("unroll") for (int m = 0; m < 4; ++m) _Pragma("unroll") for (int k = 0; k < 2; ++k) dst[m][k] = *(const PG8_LAS bf16x8*)(lds + PG8_SA(b, h) + aoff + m * 2048 + k * 1024); } while (0)
; #define PG8_LDB(dst, b, h) do { _Pragma("unroll") for (int n = 0; n < 2; ++n) _Pragma("unroll") for (int k = 0; k < 2; ++k) dst[n][k] = *(const PG8_LAS bf16x8*)(lds + PG8_SB(b, h) + boff + n * 2048 + k * 1024); } while (0)
; template <class Epi, class Sched, bool ALIGN_EPI = false, bool SP2 = false>
; __device__ __forceinline__ void gemm_phase(PG8_LAS unsigned char* lds, const Gemm g, const Sched& S, const Epi& E) {
;     ...
;         for (int t = 0; t < nt; t += 2) {
;             const bool last = (t == nt - 2);
;             const char* a1 = cA + (size_t)(t + 1) * kstep;
;             const char* a2 = last ? nA : cA + (size_t)(t + 2) * kstep; const char* b2 = last ? nB : cB + (size_t)(t + 2) * kstep;
;             const char* a3 = a2 + kstep; const char* b3 = b2 + kstep;
;             if (last && has_next) S.a_ready(nxt);
;             if constexpr (SP2) {
;             PG8_LDB(B0, 0, 0); PG8_LDB(B1, 0, 1); PG8_SCHED; PG8_LDA(At, 0, 0); PG8_STAGE(PG8_SA(1, 1), a1 + hstep, voffA);
;             PG8_WAIT_V(8); PG8_WAIT_L(0); PG8_BAR; PG8_MMA(0, 0, At, B0); PG8_MMA(0, 1, At, B1); PG8_BAR; PG8_SCHED;
;             PG8_LDA(At, 0, 1); PG8_STAGE(PG8_SB(0, 0), b2, voffB); PG8_STAGE(PG8_SB(0, 1), b2 + hstep, voffB); PG8_STAGE(PG8_SA(0, 0), a2, voffA);
;             PG8_WAIT_V(8); PG8_WAIT_L(0); PG8_BAR; PG8_MMA(1, 0, At, B0); PG8_MMA(1, 1, At, B1); PG8_BAR; PG8_SCHED;
;             PG8_LDB(B0, 1, 0); PG8_LDB(B1, 1, 1); PG8_SCHED; PG8_LDA(At, 1, 0); PG8_STAGE(PG8_SA(0, 1), a2 + hstep, voffA);
;             PG8_WAIT_V(8); PG8_WAIT_L(0); PG8_BAR; PG8_MMA(0, 0, At, B0); PG8_MMA(0, 1, At, B1); PG8_BAR; PG8_SCHED;
;             PG8_LDA(At, 1, 1); PG8_STAGE(PG8_SB(1, 0), b3, voffB); PG8_STAGE(PG8_SB(1, 1), b3 + hstep, voffB); PG8_STAGE(PG8_SA(1, 0), a3, voffA);
;             PG8_WAIT_V(8); PG8_WAIT_L(0); PG8_BAR; PG8_MMA(1, 0, At, B0); PG8_MMA(1, 1, At, B1); PG8_BAR; PG8_SCHED;
.LBB11_456:
	s_add_u32 s18, s16, 0xfff80080
	s_addc_u32 s19, s17, -1
	s_add_i32 s49, 0, 0x10000
	s_cmp_eq_u32 s48, 28
	s_cselect_b32 s21, s11, s19
	s_cselect_b32 s20, s44, s18
	v_add_u32_e32 v144, s49, v147
	s_cselect_b32 s19, s9, s47
	s_cselect_b32 s18, s45, s46
	s_add_i32 s52, 0, 0x14000
	ds_read_b128 v[150:153], v144
	ds_read_b128 v[154:157], v144 offset:1024
	ds_read_b128 v[158:161], v144 offset:2048
	ds_read_b128 v[162:165], v144 offset:3072
	v_add_u32_e32 v144, s52, v147
	ds_read_b128 v[166:169], v144
	ds_read_b128 v[170:173], v144 offset:1024
	ds_read_b128 v[174:177], v144 offset:2048
	ds_read_b128 v[178:181], v144 offset:3072
	v_lshl_add_u64 v[144:145], s[16:17], 0, v[140:141]
	s_add_i32 m0, s29, 0xc000
	ds_read_b128 v[198:201], v149
	ds_read_b128 v[202:205], v149 offset:1024
	ds_read_b128 v[220:223], v149 offset:2048
	ds_read_b128 v[224:227], v149 offset:3072
	ds_read_b128 v[228:231], v149 offset:4096
	ds_read_b128 v[232:235], v149 offset:5120
	ds_read_b128 v[236:239], v149 offset:6144
	ds_read_b128 v[240:243], v149 offset:7168
	global_load_lds_dwordx4 v[144:145], off
	v_lshl_add_u64 v[144:145], s[16:17], 0, v[142:143]
	s_add_i32 m0, s29, 0xe000
	s_nop 0
	global_load_lds_dwordx4 v[144:145], off
	s_waitcnt vmcnt(8)
	s_waitcnt lgkmcnt(0)
	s_barrier
	s_setprio 1
	s_waitcnt lgkmcnt(0)
	v_mfma_f32_16x16x32_bf16 v[124:127], v[150:153], v[198:201], v[124:127]
	v_mfma_f32_16x16x32_bf16 v[124:127], v[154:157], v[202:205], v[124:127]
	v_mfma_f32_16x16x32_bf16 v[116:119], v[162:165], v[202:205], v[116:119]
	v_mfma_f32_16x16x32_bf16 v[116:119], v[158:161], v[198:201], v[116:119]
	v_mfma_f32_16x16x32_bf16 v[108:111], v[150:153], v[220:223], v[108:111]
	v_mfma_f32_16x16x32_bf16 v[108:111], v[154:157], v[224:227], v[108:111]
	v_mfma_f32_16x16x32_bf16 v[100:103], v[162:165], v[224:227], v[100:103]
	v_mfma_f32_16x16x32_bf16 v[100:103], v[158:161], v[220:223], v[100:103]
	v_mfma_f32_16x16x32_bf16 v[92:95], v[150:153], v[228:231], v[92:95]
	v_mfma_f32_16x16x32_bf16 v[92:95], v[154:157], v[232:235], v[92:95]
	v_mfma_f32_16x16x32_bf16 v[84:87], v[162:165], v[232:235], v[84:87]
	v_mfma_f32_16x16x32_bf16 v[84:87], v[158:161], v[228:231], v[84:87]
	v_mfma_f32_16x16x32_bf16 v[76:79], v[150:153], v[236:239], v[76:79]
	v_mfma_f32_16x16x32_bf16 v[76:79], v[154:157], v[240:243], v[76:79]
	v_mfma_f32_16x16x32_bf16 v[68:71], v[162:165], v[240:243], v[68:71]
	v_mfma_f32_16x16x32_bf16 v[68:71], v[158:161], v[236:239], v[68:71]
	s_setprio 0
	s_setprio 1
	v_mfma_f32_16x16x32_bf16 v[128:131], v[166:169], v[198:201], v[128:131]
	v_mfma_f32_16x16x32_bf16 v[128:131], v[170:173], v[202:205], v[128:131]
	v_mfma_f32_16x16x32_bf16 v[120:123], v[178:181], v[202:205], v[120:123]
	v_mfma_f32_16x16x32_bf16 v[120:123], v[174:177], v[198:201], v[120:123]
	v_mfma_f32_16x16x32_bf16 v[112:115], v[166:169], v[220:223], v[112:115]
	v_mfma_f32_16x16x32_bf16 v[112:115], v[170:173], v[224:227], v[112:115]
	v_mfma_f32_16x16x32_bf16 v[104:107], v[178:181], v[224:227], v[104:107]
	v_mfma_f32_16x16x32_bf16 v[104:107], v[174:177], v[220:223], v[104:107]
	v_mfma_f32_16x16x32_bf16 v[96:99], v[166:169], v[228:231], v[96:99]
	v_mfma_f32_16x16x32_bf16 v[96:99], v[170:173], v[232:235], v[96:99]
	v_mfma_f32_16x16x32_bf16 v[88:91], v[178:181], v[232:235], v[88:91]
	v_mfma_f32_16x16x32_bf16 v[88:91], v[174:177], v[228:231], v[88:91]
	v_mfma_f32_16x16x32_bf16 v[80:83], v[166:169], v[236:239], v[80:83]
	v_mfma_f32_16x16x32_bf16 v[80:83], v[170:173], v[240:243], v[80:83]
	v_mfma_f32_16x16x32_bf16 v[72:75], v[178:181], v[240:243], v[72:75]
	v_mfma_f32_16x16x32_bf16 v[72:75], v[174:177], v[236:239], v[72:75]
	s_setprio 0
	s_barrier
	s_add_i32 s49, s49, s27
	v_lshl_add_u64 v[144:145], s[18:19], 0, v[2:3]
	s_mov_b32 m0, s49
	ds_read_b128 v[198:201], v149 offset:16384
	ds_read_b128 v[202:205], v149 offset:17408
	ds_read_b128 v[220:223], v149 offset:18432
	ds_read_b128 v[224:227], v149 offset:19456
	ds_read_b128 v[228:231], v149 offset:20480
	ds_read_b128 v[232:235], v149 offset:21504
	ds_read_b128 v[236:239], v149 offset:22528
	ds_read_b128 v[240:243], v149 offset:23552
	global_load_lds_dwordx4 v[144:145], off
	s_add_i32 m0, s49, 0x2000
	s_add_u32 s50, s18, 0x80000
	v_lshl_add_u64 v[206:207], s[18:19], 0, v[132:133]
	s_addc_u32 s51, s19, 0
	s_add_i32 s49, s52, s27
	global_load_lds_dwordx4 v[206:207], off
	v_lshl_add_u64 v[244:245], s[50:51], 0, v[2:3]
	s_mov_b32 m0, s49
	v_lshl_add_u64 v[246:247], s[20:21], 0, v[134:135]
	global_load_lds_dwordx4 v[244:245], off
	v_lshl_add_u64 v[244:245], s[50:51], 0, v[132:133]
	s_add_i32 m0, s49, 0x2000
	s_nop 0
	global_load_lds_dwordx4 v[244:245], off
	v_lshl_add_u64 v[244:245], s[20:21], 0, v[136:137]
	s_mov_b32 m0, s29
	s_nop 0
	global_load_lds_dwordx4 v[244:245], off
	s_mov_b32 m0, s30
	s_nop 0
	global_load_lds_dwordx4 v[246:247], off
	s_waitcnt vmcnt(8)
	s_waitcnt lgkmcnt(0)
	s_barrier
; #define PG8_STAGE(bufoff, gbase, voff) do { _Pragma("unroll") for (int _i = 0; _i < 2; ++_i) \
;         __builtin_amdgcn_global_load_lds((const unsigned*)((const char*)(gbase) + (voff)[_i]), (PG8_LAS unsigned*)(lds + (bufoff) + ldsw + _i * 8192), 16, 0, 0); } while (0)
; #define PG8_LDA(dst, b, h) do { _Pragma("unroll") for (int m = 0; m < 4; ++m) _Pragma("unroll") for (int k = 0; k < 2; ++k) dst[m][k] = *(const PG8_LAS bf16x8*)(lds + PG8_SA(b, h) + aoff + m * 2048 + k * 1024); } while (0)
; #define PG8_LDB(dst, b, h) do { _Pragma("unroll") for (int n = 0; n < 2; ++n) _Pragma("unroll") for (int k = 0; k < 2; ++k) dst[n][k] = *(const PG8_LAS bf16x8*)(lds + PG8_SB(b, h) + boff + n * 2048 + k * 1024); } while (0)
; #define PG8_MMA(ai, bj, At, Bt) do { __builtin_amdgcn_s_setprio(1); _Pragma("unroll") for (int m = 0; m < 4; ++m) _Pragma("unroll") for (int n = 0; n < 2; ++n) _Pragma("unroll") for (int k = 0; k < 2; ++k) \
;         acc[ai][bj][m][n] = __builtin_amdgcn_mfma_f32_16x16x32_bf16(Bt[n][k], At[m][k], acc[ai][bj][m][n], 0, 0, 0); __builtin_amdgcn_s_setprio(0); } while (0)
; #define PG8_WAIT_V(n) asm volatile("s_waitcnt vmcnt(" #n ")" ::: "memory")
; #define PG8_WAIT_L(n) asm volatile("s_waitcnt lgkmcnt(" #n ")" ::: "memory")
; #define PG8_BAR __builtin_amdgcn_s_barrier()
; #define PG8_SCHED __builtin_amdgcn_sched_barrier(0)
; template <class Epi, class Sched, bool ALIGN_EPI = false, bool SP2 = false>
; __device__ __forceinline__ void gemm_phase(PG8_LAS unsigned char* lds, const Gemm g, const Sched& S, const Epi& E) {
;     ...
;             PG8_LDB(B0, 0, 0); PG8_LDB(B1, 0, 1); PG8_SCHED; PG8_LDA(At, 0, 0); PG8_STAGE(PG8_SA(1, 1), a1 + hstep, voffA);
;             PG8_WAIT_V(8); PG8_WAIT_L(0); PG8_BAR; PG8_MMA(0, 0, At, B0); PG8_MMA(0, 1, At, B1); PG8_BAR; PG8_SCHED;
;             PG8_LDA(At, 0, 1); PG8_STAGE(PG8_SB(0, 0), b2, voffB); PG8_STAGE(PG8_SB(0, 1), b2 + hstep, voffB); PG8_STAGE(PG8_SA(0, 0), a2, voffA);
;             PG8_WAIT_V(8); PG8_WAIT_L(0); PG8_BAR; PG8_MMA(1, 0, At, B0); PG8_MMA(1, 1, At, B1); PG8_BAR; PG8_SCHED;
;             PG8_LDB(B0, 1, 0); PG8_LDB(B1, 1, 1); PG8_SCHED; PG8_LDA(At, 1, 0); PG8_STAGE(PG8_SA(0, 1), a2 + hstep, voffA);
;             PG8_WAIT_V(8); PG8_WAIT_L(0); PG8_BAR; PG8_MMA(0, 0, At, B0); PG8_MMA(0, 1, At, B1); PG8_BAR; PG8_SCHED;
	s_setprio 1
	s_waitcnt lgkmcnt(0)
	v_mfma_f32_16x16x32_bf16 v[60:63], v[150:153], v[198:201], v[60:63]
	v_mfma_f32_16x16x32_bf16 v[60:63], v[154:157], v[202:205], v[60:63]
	v_mfma_f32_16x16x32_bf16 v[52:55], v[162:165], v[202:205], v[52:55]
	v_mfma_f32_16x16x32_bf16 v[52:55], v[158:161], v[198:201], v[52:55]
	v_mfma_f32_16x16x32_bf16 v[44:47], v[150:153], v[220:223], v[44:47]
	v_mfma_f32_16x16x32_bf16 v[44:47], v[154:157], v[224:227], v[44:47]
	v_mfma_f32_16x16x32_bf16 v[36:39], v[162:165], v[224:227], v[36:39]
	v_mfma_f32_16x16x32_bf16 v[36:39], v[158:161], v[220:223], v[36:39]
	v_mfma_f32_16x16x32_bf16 v[28:31], v[150:153], v[228:231], v[28:31]
	v_mfma_f32_16x16x32_bf16 v[28:31], v[154:157], v[232:235], v[28:31]
	v_mfma_f32_16x16x32_bf16 v[20:23], v[162:165], v[232:235], v[20:23]
	v_mfma_f32_16x16x32_bf16 v[20:23], v[158:161], v[228:231], v[20:23]
	v_mfma_f32_16x16x32_bf16 v[12:15], v[150:153], v[236:239], v[12:15]
	v_mfma_f32_16x16x32_bf16 v[12:15], v[154:157], v[240:243], v[12:15]
	v_mfma_f32_16x16x32_bf16 v[4:7], v[162:165], v[240:243], v[4:7]
	v_mfma_f32_16x16x32_bf16 v[4:7], v[158:161], v[236:239], v[4:7]
	s_setprio 0
	s_setprio 1
	v_mfma_f32_16x16x32_bf16 v[64:67], v[166:169], v[198:201], v[64:67]
	v_mfma_f32_16x16x32_bf16 v[64:67], v[170:173], v[202:205], v[64:67]
	v_mfma_f32_16x16x32_bf16 v[56:59], v[178:181], v[202:205], v[56:59]
	v_mfma_f32_16x16x32_bf16 v[56:59], v[174:177], v[198:201], v[56:59]
	v_mfma_f32_16x16x32_bf16 v[48:51], v[166:169], v[220:223], v[48:51]
	v_mfma_f32_16x16x32_bf16 v[48:51], v[170:173], v[224:227], v[48:51]
	v_mfma_f32_16x16x32_bf16 v[40:43], v[178:181], v[224:227], v[40:43]
	v_mfma_f32_16x16x32_bf16 v[40:43], v[174:177], v[220:223], v[40:43]
	v_mfma_f32_16x16x32_bf16 v[32:35], v[166:169], v[228:231], v[32:35]
	v_mfma_f32_16x16x32_bf16 v[32:35], v[170:173], v[232:235], v[32:35]
	v_mfma_f32_16x16x32_bf16 v[24:27], v[178:181], v[232:235], v[24:27]
	v_mfma_f32_16x16x32_bf16 v[24:27], v[174:177], v[228:231], v[24:27]
	v_mfma_f32_16x16x32_bf16 v[16:19], v[166:169], v[236:239], v[16:19]
	v_mfma_f32_16x16x32_bf16 v[16:19], v[170:173], v[240:243], v[16:19]
	v_mfma_f32_16x16x32_bf16 v[8:11], v[178:181], v[240:243], v[8:11]
	v_mfma_f32_16x16x32_bf16 v[8:11], v[174:177], v[236:239], v[8:11]
	s_setprio 0
	s_barrier
	s_add_i32 s49, 0, 0x18000
	s_add_i32 s50, 0, 0x1c000
	v_add_u32_e32 v162, s49, v147
	v_add_u32_e32 v178, s50, v147
	ds_read_b128 v[150:153], v162
	ds_read_b128 v[154:157], v162 offset:1024
	ds_read_b128 v[158:161], v162 offset:2048
	ds_read_b128 v[162:165], v162 offset:3072
	ds_read_b128 v[166:169], v178
	ds_read_b128 v[170:173], v178 offset:1024
	ds_read_b128 v[174:177], v178 offset:2048
	ds_read_b128 v[178:181], v178 offset:3072
	s_add_u32 s20, s20, 0x80000
	s_addc_u32 s21, s21, 0
	s_mov_b32 m0, s33
	v_lshl_add_u64 v[196:197], s[20:21], 0, v[136:137]
	ds_read_b128 v[198:201], v149 offset:32768
	ds_read_b128 v[202:205], v149 offset:33792
	ds_read_b128 v[220:223], v149 offset:34816
	ds_read_b128 v[224:227], v149 offset:35840
	ds_read_b128 v[228:231], v149 offset:36864
	ds_read_b128 v[232:235], v149 offset:37888
	ds_read_b128 v[236:239], v149 offset:38912
	ds_read_b128 v[240:243], v149 offset:39936
	global_load_lds_dwordx4 v[196:197], off
	v_lshl_add_u64 v[196:197], s[20:21], 0, v[134:135]
	s_mov_b32 m0, s38
	s_nop 0
	global_load_lds_dwordx4 v[196:197], off
	s_waitcnt vmcnt(8)
	s_waitcnt lgkmcnt(0)
	s_barrier
	s_setprio 1
	s_waitcnt lgkmcnt(0)
	v_mfma_f32_16x16x32_bf16 v[124:127], v[150:153], v[198:201], v[124:127]
	v_mfma_f32_16x16x32_bf16 v[124:127], v[154:157], v[202:205], v[124:127]
	v_mfma_f32_16x16x32_bf16 v[116:119], v[162:165], v[202:205], v[116:119]
	v_mfma_f32_16x16x32_bf16 v[116:119], v[158:161], v[198:201], v[116:119]
	v_mfma_f32_16x16x32_bf16 v[108:111], v[150:153], v[220:223], v[108:111]
	v_mfma_f32_16x16x32_bf16 v[108:111], v[154:157], v[224:227], v[108:111]
	v_mfma_f32_16x16x32_bf16 v[100:103], v[162:165], v[224:227], v[100:103]
	v_mfma_f32_16x16x32_bf16 v[100:103], v[158:161], v[220:223], v[100:103]
	v_mfma_f32_16x16x32_bf16 v[92:95], v[150:153], v[228:231], v[92:95]
	v_mfma_f32_16x16x32_bf16 v[92:95], v[154:157], v[232:235], v[92:95]
	v_mfma_f32_16x16x32_bf16 v[84:87], v[162:165], v[232:235], v[84:87]
	v_mfma_f32_16x16x32_bf16 v[84:87], v[158:161], v[228:231], v[84:87]
	v_mfma_f32_16x16x32_bf16 v[76:79], v[150:153], v[236:239], v[76:79]
	v_mfma_f32_16x16x32_bf16 v[76:79], v[154:157], v[240:243], v[76:79]
	v_mfma_f32_16x16x32_bf16 v[68:71], v[162:165], v[240:243], v[68:71]
	v_mfma_f32_16x16x32_bf16 v[68:71], v[158:161], v[236:239], v[68:71]
	s_setprio 0
	s_setprio 1
	v_mfma_f32_16x16x32_bf16 v[128:131], v[166:169], v[198:201], v[128:131]
	v_mfma_f32_16x16x32_bf16 v[128:131], v[170:173], v[202:205], v[128:131]
	v_mfma_f32_16x16x32_bf16 v[120:123], v[178:181], v[202:205], v[120:123]
	v_mfma_f32_16x16x32_bf16 v[120:123], v[174:177], v[198:201], v[120:123]
	v_mfma_f32_16x16x32_bf16 v[112:115], v[166:169], v[220:223], v[112:115]
	v_mfma_f32_16x16x32_bf16 v[112:115], v[170:173], v[224:227], v[112:115]
	v_mfma_f32_16x16x32_bf16 v[104:107], v[178:181], v[224:227], v[104:107]
	v_mfma_f32_16x16x32_bf16 v[104:107], v[174:177], v[220:223], v[104:107]
	v_mfma_f32_16x16x32_bf16 v[96:99], v[166:169], v[228:231], v[96:99]
	v_mfma_f32_16x16x32_bf16 v[96:99], v[170:173], v[232:235], v[96:99]
	v_mfma_f32_16x16x32_bf16 v[88:91], v[178:181], v[232:235], v[88:91]
	v_mfma_f32_16x16x32_bf16 v[88:91], v[174:177], v[228:231], v[88:91]
	v_mfma_f32_16x16x32_bf16 v[80:83], v[166:169], v[236:239], v[80:83]
	v_mfma_f32_16x16x32_bf16 v[80:83], v[170:173], v[240:243], v[80:83]
	v_mfma_f32_16x16x32_bf16 v[72:75], v[178:181], v[240:243], v[72:75]
	v_mfma_f32_16x16x32_bf16 v[72:75], v[174:177], v[236:239], v[72:75]
	s_setprio 0
	s_barrier
; #define PG8_STAGE(bufoff, gbase, voff) do { _Pragma("unroll") for (int _i = 0; _i < 2; ++_i) \
;         __builtin_amdgcn_global_load_lds((const unsigned*)((const char*)(gbase) + (voff)[_i]), (PG8_LAS unsigned*)(lds + (bufoff) + ldsw + _i * 8192), 16, 0, 0); } while (0)
; #define PG8_LDA(dst, b, h) do { _Pragma("unroll") for (int m = 0; m < 4; ++m) _Pragma("unroll") for (int k = 0; k < 2; ++k) dst[m][k] = *(const PG8_LAS bf16x8*)(lds + PG8_SA(b, h) + aoff + m * 2048 + k * 1024); } while (0)
; #define PG8_MMA(ai, bj, At, Bt) do { __builtin_amdgcn_s_setprio(1); _Pragma("unroll") for (int m = 0; m < 4; ++m) _Pragma("unroll") for (int n = 0; n < 2; ++n) _Pragma("unroll") for (int k = 0; k < 2; ++k) \
;         acc[ai][bj][m][n] = __builtin_amdgcn_mfma_f32_16x16x32_bf16(Bt[n][k], At[m][k], acc[ai][bj][m][n], 0, 0, 0); __builtin_amdgcn_s_setprio(0); } while (0)
; #define PG8_WAIT_V(n) asm volatile("s_waitcnt vmcnt(" #n ")" ::: "memory")
; #define PG8_WAIT_L(n) asm volatile("s_waitcnt lgkmcnt(" #n ")" ::: "memory")
; #define PG8_BAR __builtin_amdgcn_s_barrier()
; #define PG8_SCHED __builtin_amdgcn_sched_barrier(0)
; template <class Epi, class Sched, bool ALIGN_EPI = false, bool SP2 = false>
; __device__ __forceinline__ void gemm_phase(PG8_LAS unsigned char* lds, const Gemm g, const Sched& S, const Epi& E) {
;     ...
;             PG8_WAIT_V(8); PG8_WAIT_L(0); PG8_BAR; PG8_MMA(0, 0, At, B0); PG8_MMA(0, 1, At, B1); PG8_BAR; PG8_SCHED;
;             PG8_LDA(At, 1, 1); PG8_STAGE(PG8_SB(1, 0), b3, voffB); PG8_STAGE(PG8_SB(1, 1), b3 + hstep, voffB); PG8_STAGE(PG8_SA(1, 0), a3, voffA);
;             PG8_WAIT_V(8); PG8_WAIT_L(0); PG8_BAR; PG8_MMA(1, 0, At, B0); PG8_MMA(1, 1, At, B1); PG8_BAR; PG8_SCHED;
	s_add_i32 s20, s49, s27
	v_lshl_add_u64 v[144:145], v[144:145], 0, s[34:35]
	s_mov_b32 m0, s20
	ds_read_b128 v[198:201], v149 offset:49152
	ds_read_b128 v[202:205], v149 offset:50176
	ds_read_b128 v[220:223], v149 offset:51200
	ds_read_b128 v[224:227], v149 offset:52224
	ds_read_b128 v[228:231], v149 offset:53248
	ds_read_b128 v[232:235], v149 offset:54272
	ds_read_b128 v[236:239], v149 offset:55296
	ds_read_b128 v[240:243], v149 offset:56320
	global_load_lds_dwordx4 v[144:145], off
	s_add_i32 m0, s20, 0x2000
	s_add_u32 s18, s18, 0x80080
	v_lshl_add_u64 v[144:145], v[206:207], 0, s[34:35]
	s_addc_u32 s19, s19, 0
	s_add_i32 s20, s50, s27
	global_load_lds_dwordx4 v[144:145], off
	v_lshl_add_u64 v[144:145], s[18:19], 0, v[2:3]
	s_mov_b32 m0, s20
	s_nop 0
	global_load_lds_dwordx4 v[144:145], off
	v_lshl_add_u64 v[144:145], s[18:19], 0, v[132:133]
	s_add_i32 m0, s20, 0x2000
	s_nop 0
	global_load_lds_dwordx4 v[144:145], off
	v_lshl_add_u64 v[144:145], v[244:245], 0, s[34:35]
	s_mov_b32 m0, s39
	s_nop 0
	global_load_lds_dwordx4 v[144:145], off
	v_lshl_add_u64 v[144:145], v[246:247], 0, s[34:35]
	s_mov_b32 m0, s40
	s_nop 0
	global_load_lds_dwordx4 v[144:145], off
	s_waitcnt vmcnt(8)
	s_waitcnt lgkmcnt(0)
	s_barrier
	s_setprio 1
	s_waitcnt lgkmcnt(0)
	v_mfma_f32_16x16x32_bf16 v[60:63], v[150:153], v[198:201], v[60:63]
	v_mfma_f32_16x16x32_bf16 v[60:63], v[154:157], v[202:205], v[60:63]
	v_mfma_f32_16x16x32_bf16 v[52:55], v[162:165], v[202:205], v[52:55]
	v_mfma_f32_16x16x32_bf16 v[52:55], v[158:161], v[198:201], v[52:55]
	v_mfma_f32_16x16x32_bf16 v[44:47], v[150:153], v[220:223], v[44:47]
	v_mfma_f32_16x16x32_bf16 v[44:47], v[154:157], v[224:227], v[44:47]
	v_mfma_f32_16x16x32_bf16 v[36:39], v[162:165], v[224:227], v[36:39]
	v_mfma_f32_16x16x32_bf16 v[36:39], v[158:161], v[220:223], v[36:39]
	v_mfma_f32_16x16x32_bf16 v[28:31], v[150:153], v[228:231], v[28:31]
	v_mfma_f32_16x16x32_bf16 v[28:31], v[154:157], v[232:235], v[28:31]
	v_mfma_f32_16x16x32_bf16 v[20:23], v[162:165], v[232:235], v[20:23]
	v_mfma_f32_16x16x32_bf16 v[20:23], v[158:161], v[228:231], v[20:23]
	v_mfma_f32_16x16x32_bf16 v[12:15], v[150:153], v[236:239], v[12:15]
	v_mfma_f32_16x16x32_bf16 v[12:15], v[154:157], v[240:243], v[12:15]
	v_mfma_f32_16x16x32_bf16 v[4:7], v[162:165], v[240:243], v[4:7]
	v_mfma_f32_16x16x32_bf16 v[4:7], v[158:161], v[236:239], v[4:7]
	s_setprio 0
	s_setprio 1
	v_mfma_f32_16x16x32_bf16 v[64:67], v[166:169], v[198:201], v[64:67]
	v_mfma_f32_16x16x32_bf16 v[64:67], v[170:173], v[202:205], v[64:67]
	v_mfma_f32_16x16x32_bf16 v[56:59], v[178:181], v[202:205], v[56:59]
	v_mfma_f32_16x16x32_bf16 v[56:59], v[174:177], v[198:201], v[56:59]
	v_mfma_f32_16x16x32_bf16 v[48:51], v[166:169], v[220:223], v[48:51]
	v_mfma_f32_16x16x32_bf16 v[48:51], v[170:173], v[224:227], v[48:51]
	v_mfma_f32_16x16x32_bf16 v[40:43], v[178:181], v[224:227], v[40:43]
	v_mfma_f32_16x16x32_bf16 v[40:43], v[174:177], v[220:223], v[40:43]
	v_mfma_f32_16x16x32_bf16 v[32:35], v[166:169], v[228:231], v[32:35]
	v_mfma_f32_16x16x32_bf16 v[32:35], v[170:173], v[232:235], v[32:35]
	v_mfma_f32_16x16x32_bf16 v[24:27], v[178:181], v[232:235], v[24:27]
	v_mfma_f32_16x16x32_bf16 v[24:27], v[174:177], v[228:231], v[24:27]
	v_mfma_f32_16x16x32_bf16 v[16:19], v[166:169], v[236:239], v[16:19]
	v_mfma_f32_16x16x32_bf16 v[16:19], v[170:173], v[240:243], v[16:19]
	v_mfma_f32_16x16x32_bf16 v[8:11], v[178:181], v[240:243], v[8:11]
	v_mfma_f32_16x16x32_bf16 v[8:11], v[174:177], v[236:239], v[8:11]
	s_setprio 0
	s_barrier
	s_add_i32 s48, s48, 2
	s_add_u32 s16, s16, 0x100
	s_addc_u32 s17, s17, 0
	s_add_u32 s46, s46, 0x100
	s_addc_u32 s47, s47, 0
	s_cmp_gt_u32 s48, 29
	s_cbranch_scc0 .LBB11_456
	s_and_b64 vcc, exec, s[6:7]
	s_cbranch_vccz .LBB11_459
	s_barrier

; #define PG8_STAGE(bufoff, gbase, voff) do { _Pragma("unroll") for (int _i = 0; _i < 2; ++_i) \
;         __builtin_amdgcn_global_load_lds((const unsigned*)((const char*)(gbase) + (voff)[_i]), (PG8_LAS unsigned*)(lds + (bufoff) + ldsw + _i * 8192), 16, 0, 0); } while (0)
; #define PG8_LDA(dst, b, h) do { _Pragma("unroll") for (int m = 0; m < 4; ++m) _Pragma("unroll") for (int k = 0; k < 2; ++k) dst[m][k] = *(const PG8_LAS bf16x8*)(lds + PG8_SA(b, h) + aoff + m * 2048 + k * 1024); } while (0)
; #define PG8_LDB(dst, b, h) do { _Pragma("unroll") for (int n = 0; n < 2; ++n) _Pragma("unroll") for (int k = 0; k < 2; ++k) dst[n][k] = *(const PG8_LAS bf16x8*)(lds + PG8_SB(b, h) + boff + n * 2048 + k * 1024); } while (0)
; template <class Epi, class Sched, bool ALIGN_EPI = false, bool SP2 = false>
; __device__ __forceinline__ void gemm_phase(PG8_LAS unsigned char* lds, const Gemm g, const Sched& S, const Epi& E) {
;     ...
;         for (int t = 0; t < nt; t += 2) {
;             const bool last = (t == nt - 2);
;             const char* a1 = cA + (size_t)(t + 1) * kstep;
;             const char* a2 = last ? nA : cA + (size_t)(t + 2) * kstep; const char* b2 = last ? nB : cB + (size_t)(t + 2) * kstep;
;             const char* a3 = a2 + kstep; const char* b3 = b2 + kstep;
;             if (last && has_next) S.a_ready(nxt);
;             if constexpr (SP2) {
;             PG8_LDB(B0, 0, 0); PG8_LDB(B1, 0, 1); PG8_SCHED; PG8_LDA(At, 0, 0); PG8_STAGE(PG8_SA(1, 1), a1 + hstep, voffA);
;             PG8_WAIT_V(8); PG8_WAIT_L(0); PG8_BAR; PG8_MMA(0, 0, At, B0); PG8_MMA(0, 1, At, B1); PG8_BAR; PG8_SCHED;
;             PG8_LDA(At, 0, 1); PG8_STAGE(PG8_SB(0, 0), b2, voffB); PG8_STAGE(PG8_SB(0, 1), b2 + hstep, voffB); PG8_STAGE(PG8_SA(0, 0), a2, voffA);
;             PG8_WAIT_V(8); PG8_WAIT_L(0); PG8_BAR; PG8_MMA(1, 0, At, B0); PG8_MMA(1, 1, At, B1); PG8_BAR; PG8_SCHED;
;             PG8_LDB(B0, 1, 0); PG8_LDB(B1, 1, 1); PG8_SCHED; PG8_LDA(At, 1, 0); PG8_STAGE(PG8_SA(0, 1), a2 + hstep, voffA);
;             PG8_WAIT_V(8); PG8_WAIT_L(0); PG8_BAR; PG8_MMA(0, 0, At, B0); PG8_MMA(0, 1, At, B1); PG8_BAR; PG8_SCHED;
;             PG8_LDA(At, 1, 1); PG8_STAGE(PG8_SB(1, 0), b3, voffB); PG8_STAGE(PG8_SB(1, 1), b3 + hstep, voffB); PG8_STAGE(PG8_SA(1, 0), a3, voffA);
;             PG8_WAIT_V(8); PG8_WAIT_L(0); PG8_BAR; PG8_MMA(1, 0, At, B0); PG8_MMA(1, 1, At, B1); PG8_BAR; PG8_SCHED;
.LBB11_638:
	s_add_u32 s20, s18, 0xfff80080
	s_addc_u32 s21, s19, -1
	s_add_i32 s49, 0, 0x10000
	s_cmp_eq_u32 s48, 28
	s_cselect_b32 s23, s13, s21
	s_cselect_b32 s22, s44, s20
	v_add_u32_e32 v144, s49, v147
	s_cselect_b32 s21, s11, s47
	s_cselect_b32 s20, s45, s46
	s_add_i32 s52, 0, 0x14000
	ds_read_b128 v[150:153], v144
	ds_read_b128 v[154:157], v144 offset:1024
	ds_read_b128 v[158:161], v144 offset:2048
	ds_read_b128 v[162:165], v144 offset:3072
	v_add_u32_e32 v144, s52, v147
	ds_read_b128 v[166:169], v144
	ds_read_b128 v[170:173], v144 offset:1024
	ds_read_b128 v[174:177], v144 offset:2048
	ds_read_b128 v[178:181], v144 offset:3072
	v_lshl_add_u64 v[144:145], s[18:19], 0, v[140:141]
	s_add_i32 m0, s33, 0xc000
	ds_read_b128 v[198:201], v149
	ds_read_b128 v[202:205], v149 offset:1024
	ds_read_b128 v[220:223], v149 offset:2048
	ds_read_b128 v[224:227], v149 offset:3072
	ds_read_b128 v[228:231], v149 offset:4096
	ds_read_b128 v[232:235], v149 offset:5120
	ds_read_b128 v[236:239], v149 offset:6144
	ds_read_b128 v[240:243], v149 offset:7168
	global_load_lds_dwordx4 v[144:145], off
	v_lshl_add_u64 v[144:145], s[18:19], 0, v[142:143]
	s_add_i32 m0, s33, 0xe000
	s_nop 0
	global_load_lds_dwordx4 v[144:145], off
	s_waitcnt vmcnt(8)
	s_waitcnt lgkmcnt(0)
	s_barrier
	s_setprio 1
	s_waitcnt lgkmcnt(0)
	v_mfma_f32_16x16x32_bf16 v[128:131], v[150:153], v[198:201], v[128:131]
	v_mfma_f32_16x16x32_bf16 v[128:131], v[154:157], v[202:205], v[128:131]
	v_mfma_f32_16x16x32_bf16 v[124:127], v[162:165], v[202:205], v[124:127]
	v_mfma_f32_16x16x32_bf16 v[124:127], v[158:161], v[198:201], v[124:127]
	v_mfma_f32_16x16x32_bf16 v[120:123], v[150:153], v[220:223], v[120:123]
	v_mfma_f32_16x16x32_bf16 v[120:123], v[154:157], v[224:227], v[120:123]
	v_mfma_f32_16x16x32_bf16 v[112:115], v[162:165], v[224:227], v[112:115]
	v_mfma_f32_16x16x32_bf16 v[112:115], v[158:161], v[220:223], v[112:115]
	v_mfma_f32_16x16x32_bf16 v[104:107], v[150:153], v[228:231], v[104:107]
	v_mfma_f32_16x16x32_bf16 v[104:107], v[154:157], v[232:235], v[104:107]
	v_mfma_f32_16x16x32_bf16 v[96:99], v[162:165], v[232:235], v[96:99]
	v_mfma_f32_16x16x32_bf16 v[96:99], v[158:161], v[228:231], v[96:99]
	v_mfma_f32_16x16x32_bf16 v[88:91], v[150:153], v[236:239], v[88:91]
	v_mfma_f32_16x16x32_bf16 v[88:91], v[154:157], v[240:243], v[88:91]
	v_mfma_f32_16x16x32_bf16 v[80:83], v[162:165], v[240:243], v[80:83]
	v_mfma_f32_16x16x32_bf16 v[80:83], v[158:161], v[236:239], v[80:83]
	s_setprio 0
	s_setprio 1
	v_mfma_f32_16x16x32_bf16 v[116:119], v[166:169], v[198:201], v[116:119]
	v_mfma_f32_16x16x32_bf16 v[116:119], v[170:173], v[202:205], v[116:119]
	v_mfma_f32_16x16x32_bf16 v[108:111], v[178:181], v[202:205], v[108:111]
	v_mfma_f32_16x16x32_bf16 v[108:111], v[174:177], v[198:201], v[108:111]
	v_mfma_f32_16x16x32_bf16 v[100:103], v[166:169], v[220:223], v[100:103]
	v_mfma_f32_16x16x32_bf16 v[100:103], v[170:173], v[224:227], v[100:103]
	v_mfma_f32_16x16x32_bf16 v[92:95], v[178:181], v[224:227], v[92:95]
	v_mfma_f32_16x16x32_bf16 v[92:95], v[174:177], v[220:223], v[92:95]
	v_mfma_f32_16x16x32_bf16 v[84:87], v[166:169], v[228:231], v[84:87]
	v_mfma_f32_16x16x32_bf16 v[84:87], v[170:173], v[232:235], v[84:87]
	v_mfma_f32_16x16x32_bf16 v[76:79], v[178:181], v[232:235], v[76:79]
	v_mfma_f32_16x16x32_bf16 v[76:79], v[174:177], v[228:231], v[76:79]
	v_mfma_f32_16x16x32_bf16 v[72:75], v[166:169], v[236:239], v[72:75]
	v_mfma_f32_16x16x32_bf16 v[72:75], v[170:173], v[240:243], v[72:75]
	v_mfma_f32_16x16x32_bf16 v[68:71], v[178:181], v[240:243], v[68:71]
	v_mfma_f32_16x16x32_bf16 v[68:71], v[174:177], v[236:239], v[68:71]
	s_setprio 0
	s_barrier
	s_add_i32 s49, s49, s30
	v_lshl_add_u64 v[144:145], s[20:21], 0, v[2:3]
	s_mov_b32 m0, s49
	ds_read_b128 v[198:201], v149 offset:16384
	ds_read_b128 v[202:205], v149 offset:17408
	ds_read_b128 v[220:223], v149 offset:18432
	ds_read_b128 v[224:227], v149 offset:19456
	ds_read_b128 v[228:231], v149 offset:20480
	ds_read_b128 v[232:235], v149 offset:21504
	ds_read_b128 v[236:239], v149 offset:22528
	ds_read_b128 v[240:243], v149 offset:23552
	global_load_lds_dwordx4 v[144:145], off
	s_add_i32 m0, s49, 0x2000
	s_add_u32 s50, s20, 0x80000
	v_lshl_add_u64 v[184:185], s[20:21], 0, v[132:133]
	s_addc_u32 s51, s21, 0
	s_add_i32 s49, s52, s30
	global_load_lds_dwordx4 v[184:185], off
	v_lshl_add_u64 v[186:187], s[50:51], 0, v[2:3]
	s_mov_b32 m0, s49
	v_lshl_add_u64 v[196:197], s[22:23], 0, v[134:135]
	global_load_lds_dwordx4 v[186:187], off
	v_lshl_add_u64 v[186:187], s[50:51], 0, v[132:133]
	s_add_i32 m0, s49, 0x2000
	s_nop 0
	global_load_lds_dwordx4 v[186:187], off
	v_lshl_add_u64 v[186:187], s[22:23], 0, v[136:137]
	s_mov_b32 m0, s33
	s_nop 0
	global_load_lds_dwordx4 v[186:187], off
	s_mov_b32 m0, s36
	s_nop 0
	global_load_lds_dwordx4 v[196:197], off
	s_waitcnt vmcnt(8)
	s_waitcnt lgkmcnt(0)
	s_barrier
; #define PG8_STAGE(bufoff, gbase, voff) do { _Pragma("unroll") for (int _i = 0; _i < 2; ++_i) \
;         __builtin_amdgcn_global_load_lds((const unsigned*)((const char*)(gbase) + (voff)[_i]), (PG8_LAS unsigned*)(lds + (bufoff) + ldsw + _i * 8192), 16, 0, 0); } while (0)
; #define PG8_LDA(dst, b, h) do { _Pragma("unroll") for (int m = 0; m < 4; ++m) _Pragma("unroll") for (int k = 0; k < 2; ++k) dst[m][k] = *(const PG8_LAS bf16x8*)(lds + PG8_SA(b, h) + aoff + m * 2048 + k * 1024); } while (0)
; #define PG8_LDB(dst, b, h) do { _Pragma("unroll") for (int n = 0; n < 2; ++n) _Pragma("unroll") for (int k = 0; k < 2; ++k) dst[n][k] = *(const PG8_LAS bf16x8*)(lds + PG8_SB(b, h) + boff + n * 2048 + k * 1024); } while (0)
; #define PG8_MMA(ai, bj, At, Bt) do { __builtin_amdgcn_s_setprio(1); _Pragma("unroll") for (int m = 0; m < 4; ++m) _Pragma("unroll") for (int n = 0; n < 2; ++n) _Pragma("unroll") for (int k = 0; k < 2; ++k) \
;         acc[ai][bj][m][n] = __builtin_amdgcn_mfma_f32_16x16x32_bf16(Bt[n][k], At[m][k], acc[ai][bj][m][n], 0, 0, 0); __builtin_amdgcn_s_setprio(0); } while (0)
; #define PG8_WAIT_V(n) asm volatile("s_waitcnt vmcnt(" #n ")" ::: "memory")
; #define PG8_WAIT_L(n) asm volatile("s_waitcnt lgkmcnt(" #n ")" ::: "memory")
; #define PG8_BAR __builtin_amdgcn_s_barrier()
; #define PG8_SCHED __builtin_amdgcn_sched_barrier(0)
; template <class Epi, class Sched, bool ALIGN_EPI = false, bool SP2 = false>
; __device__ __forceinline__ void gemm_phase(PG8_LAS unsigned char* lds, const Gemm g, const Sched& S, const Epi& E) {
;     ...
;             PG8_LDB(B0, 0, 0); PG8_LDB(B1, 0, 1); PG8_SCHED; PG8_LDA(At, 0, 0); PG8_STAGE(PG8_SA(1, 1), a1 + hstep, voffA);
;             PG8_WAIT_V(8); PG8_WAIT_L(0); PG8_BAR; PG8_MMA(0, 0, At, B0); PG8_MMA(0, 1, At, B1); PG8_BAR; PG8_SCHED;
;             PG8_LDA(At, 0, 1); PG8_STAGE(PG8_SB(0, 0), b2, voffB); PG8_STAGE(PG8_SB(0, 1), b2 + hstep, voffB); PG8_STAGE(PG8_SA(0, 0), a2, voffA);
;             PG8_WAIT_V(8); PG8_WAIT_L(0); PG8_BAR; PG8_MMA(1, 0, At, B0); PG8_MMA(1, 1, At, B1); PG8_BAR; PG8_SCHED;
;             PG8_LDB(B0, 1, 0); PG8_LDB(B1, 1, 1); PG8_SCHED; PG8_LDA(At, 1, 0); PG8_STAGE(PG8_SA(0, 1), a2 + hstep, voffA);
;             PG8_WAIT_V(8); PG8_WAIT_L(0); PG8_BAR; PG8_MMA(0, 0, At, B0); PG8_MMA(0, 1, At, B1); PG8_BAR; PG8_SCHED;
	s_setprio 1
	s_waitcnt lgkmcnt(0)
	v_mfma_f32_16x16x32_bf16 v[64:67], v[150:153], v[198:201], v[64:67]
	v_mfma_f32_16x16x32_bf16 v[64:67], v[154:157], v[202:205], v[64:67]
	v_mfma_f32_16x16x32_bf16 v[60:63], v[162:165], v[202:205], v[60:63]
	v_mfma_f32_16x16x32_bf16 v[60:63], v[158:161], v[198:201], v[60:63]
	v_mfma_f32_16x16x32_bf16 v[56:59], v[150:153], v[220:223], v[56:59]
	v_mfma_f32_16x16x32_bf16 v[56:59], v[154:157], v[224:227], v[56:59]
	v_mfma_f32_16x16x32_bf16 v[48:51], v[162:165], v[224:227], v[48:51]
	v_mfma_f32_16x16x32_bf16 v[48:51], v[158:161], v[220:223], v[48:51]
	v_mfma_f32_16x16x32_bf16 v[40:43], v[150:153], v[228:231], v[40:43]
	v_mfma_f32_16x16x32_bf16 v[40:43], v[154:157], v[232:235], v[40:43]
	v_mfma_f32_16x16x32_bf16 v[32:35], v[162:165], v[232:235], v[32:35]
	v_mfma_f32_16x16x32_bf16 v[32:35], v[158:161], v[228:231], v[32:35]
	v_mfma_f32_16x16x32_bf16 v[24:27], v[150:153], v[236:239], v[24:27]
	v_mfma_f32_16x16x32_bf16 v[24:27], v[154:157], v[240:243], v[24:27]
	v_mfma_f32_16x16x32_bf16 v[16:19], v[162:165], v[240:243], v[16:19]
	v_mfma_f32_16x16x32_bf16 v[16:19], v[158:161], v[236:239], v[16:19]
	s_setprio 0
	s_setprio 1
	v_mfma_f32_16x16x32_bf16 v[52:55], v[166:169], v[198:201], v[52:55]
	v_mfma_f32_16x16x32_bf16 v[52:55], v[170:173], v[202:205], v[52:55]
	v_mfma_f32_16x16x32_bf16 v[44:47], v[178:181], v[202:205], v[44:47]
	v_mfma_f32_16x16x32_bf16 v[44:47], v[174:177], v[198:201], v[44:47]
	v_mfma_f32_16x16x32_bf16 v[36:39], v[166:169], v[220:223], v[36:39]
	v_mfma_f32_16x16x32_bf16 v[36:39], v[170:173], v[224:227], v[36:39]
	v_mfma_f32_16x16x32_bf16 v[28:31], v[178:181], v[224:227], v[28:31]
	v_mfma_f32_16x16x32_bf16 v[28:31], v[174:177], v[220:223], v[28:31]
	v_mfma_f32_16x16x32_bf16 v[20:23], v[166:169], v[228:231], v[20:23]
	v_mfma_f32_16x16x32_bf16 v[20:23], v[170:173], v[232:235], v[20:23]
	v_mfma_f32_16x16x32_bf16 v[12:15], v[178:181], v[232:235], v[12:15]
	v_mfma_f32_16x16x32_bf16 v[12:15], v[174:177], v[228:231], v[12:15]
	v_mfma_f32_16x16x32_bf16 v[8:11], v[166:169], v[236:239], v[8:11]
	v_mfma_f32_16x16x32_bf16 v[8:11], v[170:173], v[240:243], v[8:11]
	v_mfma_f32_16x16x32_bf16 v[4:7], v[178:181], v[240:243], v[4:7]
	v_mfma_f32_16x16x32_bf16 v[4:7], v[174:177], v[236:239], v[4:7]
	s_setprio 0
	s_barrier
	s_add_i32 s49, 0, 0x18000
	s_add_i32 s50, 0, 0x1c000
	v_add_u32_e32 v162, s49, v147
	v_add_u32_e32 v178, s50, v147
	ds_read_b128 v[150:153], v162
	ds_read_b128 v[154:157], v162 offset:1024
	ds_read_b128 v[158:161], v162 offset:2048
	ds_read_b128 v[162:165], v162 offset:3072
	ds_read_b128 v[166:169], v178
	ds_read_b128 v[170:173], v178 offset:1024
	ds_read_b128 v[174:177], v178 offset:2048
	ds_read_b128 v[178:181], v178 offset:3072
	s_add_u32 s22, s22, 0x80000
	s_addc_u32 s23, s23, 0
	s_mov_b32 m0, s37
	v_lshl_add_u64 v[206:207], s[22:23], 0, v[136:137]
	ds_read_b128 v[198:201], v149 offset:32768
	ds_read_b128 v[202:205], v149 offset:33792
	ds_read_b128 v[220:223], v149 offset:34816
	ds_read_b128 v[224:227], v149 offset:35840
	ds_read_b128 v[228:231], v149 offset:36864
	ds_read_b128 v[232:235], v149 offset:37888
	ds_read_b128 v[236:239], v149 offset:38912
	ds_read_b128 v[240:243], v149 offset:39936
	global_load_lds_dwordx4 v[206:207], off
	v_lshl_add_u64 v[206:207], s[22:23], 0, v[134:135]
	s_mov_b32 m0, s38
	s_nop 0
	global_load_lds_dwordx4 v[206:207], off
	s_waitcnt vmcnt(8)
	s_waitcnt lgkmcnt(0)
	s_barrier
	s_setprio 1
	s_waitcnt lgkmcnt(0)
	v_mfma_f32_16x16x32_bf16 v[128:131], v[150:153], v[198:201], v[128:131]
	v_mfma_f32_16x16x32_bf16 v[128:131], v[154:157], v[202:205], v[128:131]
	v_mfma_f32_16x16x32_bf16 v[124:127], v[162:165], v[202:205], v[124:127]
	v_mfma_f32_16x16x32_bf16 v[124:127], v[158:161], v[198:201], v[124:127]
	v_mfma_f32_16x16x32_bf16 v[120:123], v[150:153], v[220:223], v[120:123]
	v_mfma_f32_16x16x32_bf16 v[120:123], v[154:157], v[224:227], v[120:123]
	v_mfma_f32_16x16x32_bf16 v[112:115], v[162:165], v[224:227], v[112:115]
	v_mfma_f32_16x16x32_bf16 v[112:115], v[158:161], v[220:223], v[112:115]
	v_mfma_f32_16x16x32_bf16 v[104:107], v[150:153], v[228:231], v[104:107]
	v_mfma_f32_16x16x32_bf16 v[104:107], v[154:157], v[232:235], v[104:107]
	v_mfma_f32_16x16x32_bf16 v[96:99], v[162:165], v[232:235], v[96:99]
	v_mfma_f32_16x16x32_bf16 v[96:99], v[158:161], v[228:231], v[96:99]
	v_mfma_f32_16x16x32_bf16 v[88:91], v[150:153], v[236:239], v[88:91]
	v_mfma_f32_16x16x32_bf16 v[88:91], v[154:157], v[240:243], v[88:91]
	v_mfma_f32_16x16x32_bf16 v[80:83], v[162:165], v[240:243], v[80:83]
	v_mfma_f32_16x16x32_bf16 v[80:83], v[158:161], v[236:239], v[80:83]
	s_setprio 0
	s_setprio 1
	v_mfma_f32_16x16x32_bf16 v[116:119], v[166:169], v[198:201], v[116:119]
	v_mfma_f32_16x16x32_bf16 v[116:119], v[170:173], v[202:205], v[116:119]
	v_mfma_f32_16x16x32_bf16 v[108:111], v[178:181], v[202:205], v[108:111]
	v_mfma_f32_16x16x32_bf16 v[108:111], v[174:177], v[198:201], v[108:111]
	v_mfma_f32_16x16x32_bf16 v[100:103], v[166:169], v[220:223], v[100:103]
	v_mfma_f32_16x16x32_bf16 v[100:103], v[170:173], v[224:227], v[100:103]
	v_mfma_f32_16x16x32_bf16 v[92:95], v[178:181], v[224:227], v[92:95]
	v_mfma_f32_16x16x32_bf16 v[92:95], v[174:177], v[220:223], v[92:95]
	v_mfma_f32_16x16x32_bf16 v[84:87], v[166:169], v[228:231], v[84:87]
	v_mfma_f32_16x16x32_bf16 v[84:87], v[170:173], v[232:235], v[84:87]
	v_mfma_f32_16x16x32_bf16 v[76:79], v[178:181], v[232:235], v[76:79]
	v_mfma_f32_16x16x32_bf16 v[76:79], v[174:177], v[228:231], v[76:79]
	v_mfma_f32_16x16x32_bf16 v[72:75], v[166:169], v[236:239], v[72:75]
	v_mfma_f32_16x16x32_bf16 v[72:75], v[170:173], v[240:243], v[72:75]
	v_mfma_f32_16x16x32_bf16 v[68:71], v[178:181], v[240:243], v[68:71]
	v_mfma_f32_16x16x32_bf16 v[68:71], v[174:177], v[236:239], v[68:71]
	s_setprio 0
	s_barrier
; #define PG8_STAGE(bufoff, gbase, voff) do { _Pragma("unroll") for (int _i = 0; _i < 2; ++_i) \
;         __builtin_amdgcn_global_load_lds((const unsigned*)((const char*)(gbase) + (voff)[_i]), (PG8_LAS unsigned*)(lds + (bufoff) + ldsw + _i * 8192), 16, 0, 0); } while (0)
; #define PG8_LDA(dst, b, h) do { _Pragma("unroll") for (int m = 0; m < 4; ++m) _Pragma("unroll") for (int k = 0; k < 2; ++k) dst[m][k] = *(const PG8_LAS bf16x8*)(lds + PG8_SA(b, h) + aoff + m * 2048 + k * 1024); } while (0)
; #define PG8_MMA(ai, bj, At, Bt) do { __builtin_amdgcn_s_setprio(1); _Pragma("unroll") for (int m = 0; m < 4; ++m) _Pragma("unroll") for (int n = 0; n < 2; ++n) _Pragma("unroll") for (int k = 0; k < 2; ++k) \
;         acc[ai][bj][m][n] = __builtin_amdgcn_mfma_f32_16x16x32_bf16(Bt[n][k], At[m][k], acc[ai][bj][m][n], 0, 0, 0); __builtin_amdgcn_s_setprio(0); } while (0)
; #define PG8_WAIT_V(n) asm volatile("s_waitcnt vmcnt(" #n ")" ::: "memory")
; #define PG8_WAIT_L(n) asm volatile("s_waitcnt lgkmcnt(" #n ")" ::: "memory")
; #define PG8_BAR __builtin_amdgcn_s_barrier()
; #define PG8_SCHED __builtin_amdgcn_sched_barrier(0)
; template <class Epi, class Sched, bool ALIGN_EPI = false, bool SP2 = false>
; __device__ __forceinline__ void gemm_phase(PG8_LAS unsigned char* lds, const Gemm g, const Sched& S, const Epi& E) {
;     ...
;             PG8_WAIT_V(8); PG8_WAIT_L(0); PG8_BAR; PG8_MMA(0, 0, At, B0); PG8_MMA(0, 1, At, B1); PG8_BAR; PG8_SCHED;
;             PG8_LDA(At, 1, 1); PG8_STAGE(PG8_SB(1, 0), b3, voffB); PG8_STAGE(PG8_SB(1, 1), b3 + hstep, voffB); PG8_STAGE(PG8_SA(1, 0), a3, voffA);
;             PG8_WAIT_V(8); PG8_WAIT_L(0); PG8_BAR; PG8_MMA(1, 0, At, B0); PG8_MMA(1, 1, At, B1); PG8_BAR; PG8_SCHED;
	s_add_i32 s22, s49, s30
	v_lshl_add_u64 v[144:145], v[144:145], 0, s[34:35]
	s_mov_b32 m0, s22
	ds_read_b128 v[198:201], v149 offset:49152
	ds_read_b128 v[202:205], v149 offset:50176
	ds_read_b128 v[220:223], v149 offset:51200
	ds_read_b128 v[224:227], v149 offset:52224
	ds_read_b128 v[228:231], v149 offset:53248
	ds_read_b128 v[232:235], v149 offset:54272
	ds_read_b128 v[236:239], v149 offset:55296
	ds_read_b128 v[240:243], v149 offset:56320
	global_load_lds_dwordx4 v[144:145], off
	s_add_i32 m0, s22, 0x2000
	s_add_u32 s20, s20, 0x80080
	v_lshl_add_u64 v[144:145], v[184:185], 0, s[34:35]
	s_addc_u32 s21, s21, 0
	s_add_i32 s22, s50, s30
	global_load_lds_dwordx4 v[144:145], off
	v_lshl_add_u64 v[144:145], s[20:21], 0, v[2:3]
	s_mov_b32 m0, s22
	s_nop 0
	global_load_lds_dwordx4 v[144:145], off
	v_lshl_add_u64 v[144:145], s[20:21], 0, v[132:133]
	s_add_i32 m0, s22, 0x2000
	s_nop 0
	global_load_lds_dwordx4 v[144:145], off
	v_lshl_add_u64 v[144:145], v[186:187], 0, s[34:35]
	s_mov_b32 m0, s39
	s_nop 0
	global_load_lds_dwordx4 v[144:145], off
	v_lshl_add_u64 v[144:145], v[196:197], 0, s[34:35]
	s_mov_b32 m0, s40
	s_nop 0
	global_load_lds_dwordx4 v[144:145], off
	s_waitcnt vmcnt(8)
	s_waitcnt lgkmcnt(0)
	s_barrier
	s_setprio 1
	s_waitcnt lgkmcnt(0)
	v_mfma_f32_16x16x32_bf16 v[64:67], v[150:153], v[198:201], v[64:67]
	v_mfma_f32_16x16x32_bf16 v[64:67], v[154:157], v[202:205], v[64:67]
	v_mfma_f32_16x16x32_bf16 v[60:63], v[162:165], v[202:205], v[60:63]
	v_mfma_f32_16x16x32_bf16 v[60:63], v[158:161], v[198:201], v[60:63]
	v_mfma_f32_16x16x32_bf16 v[56:59], v[150:153], v[220:223], v[56:59]
	v_mfma_f32_16x16x32_bf16 v[56:59], v[154:157], v[224:227], v[56:59]
	v_mfma_f32_16x16x32_bf16 v[48:51], v[162:165], v[224:227], v[48:51]
	v_mfma_f32_16x16x32_bf16 v[48:51], v[158:161], v[220:223], v[48:51]
	v_mfma_f32_16x16x32_bf16 v[40:43], v[150:153], v[228:231], v[40:43]
	v_mfma_f32_16x16x32_bf16 v[40:43], v[154:157], v[232:235], v[40:43]
	v_mfma_f32_16x16x32_bf16 v[32:35], v[162:165], v[232:235], v[32:35]
	v_mfma_f32_16x16x32_bf16 v[32:35], v[158:161], v[228:231], v[32:35]
	v_mfma_f32_16x16x32_bf16 v[24:27], v[150:153], v[236:239], v[24:27]
	v_mfma_f32_16x16x32_bf16 v[24:27], v[154:157], v[240:243], v[24:27]
	v_mfma_f32_16x16x32_bf16 v[16:19], v[162:165], v[240:243], v[16:19]
	v_mfma_f32_16x16x32_bf16 v[16:19], v[158:161], v[236:239], v[16:19]
	s_setprio 0
	s_setprio 1
	v_mfma_f32_16x16x32_bf16 v[52:55], v[166:169], v[198:201], v[52:55]
	v_mfma_f32_16x16x32_bf16 v[52:55], v[170:173], v[202:205], v[52:55]
	v_mfma_f32_16x16x32_bf16 v[44:47], v[178:181], v[202:205], v[44:47]
	v_mfma_f32_16x16x32_bf16 v[44:47], v[174:177], v[198:201], v[44:47]
	v_mfma_f32_16x16x32_bf16 v[36:39], v[166:169], v[220:223], v[36:39]
	v_mfma_f32_16x16x32_bf16 v[36:39], v[170:173], v[224:227], v[36:39]
	v_mfma_f32_16x16x32_bf16 v[28:31], v[178:181], v[224:227], v[28:31]
	v_mfma_f32_16x16x32_bf16 v[28:31], v[174:177], v[220:223], v[28:31]
	v_mfma_f32_16x16x32_bf16 v[20:23], v[166:169], v[228:231], v[20:23]
	v_mfma_f32_16x16x32_bf16 v[20:23], v[170:173], v[232:235], v[20:23]
	v_mfma_f32_16x16x32_bf16 v[12:15], v[178:181], v[232:235], v[12:15]
	v_mfma_f32_16x16x32_bf16 v[12:15], v[174:177], v[228:231], v[12:15]
	v_mfma_f32_16x16x32_bf16 v[8:11], v[166:169], v[236:239], v[8:11]
	v_mfma_f32_16x16x32_bf16 v[8:11], v[170:173], v[240:243], v[8:11]
	v_mfma_f32_16x16x32_bf16 v[4:7], v[178:181], v[240:243], v[4:7]
	v_mfma_f32_16x16x32_bf16 v[4:7], v[174:177], v[236:239], v[4:7]
	s_setprio 0
	s_barrier
	s_add_i32 s48, s48, 2
	s_add_u32 s18, s18, 0x100
	s_addc_u32 s19, s19, 0
	s_add_u32 s46, s46, 0x100
	s_addc_u32 s47, s47, 0
	s_cmp_gt_u32 s48, 29
	s_cbranch_scc0 .LBB11_638
	s_and_b64 vcc, exec, s[4:5]
	s_cbranch_vccz .LBB11_641
	s_barrier

; #define PG8_STAGE(bufoff, gbase, voff) do { _Pragma("unroll") for (int _i = 0; _i < 2; ++_i) \
;         __builtin_amdgcn_global_load_lds((const unsigned*)((const char*)(gbase) + (voff)[_i]), (PG8_LAS unsigned*)(lds + (bufoff) + ldsw + _i * 8192), 16, 0, 0); } while (0)
; #define PG8_LDA(dst, b, h) do { _Pragma("unroll") for (int m = 0; m < 4; ++m) _Pragma("unroll") for (int k = 0; k < 2; ++k) dst[m][k] = *(const PG8_LAS bf16x8*)(lds + PG8_SA(b, h) + aoff + m * 2048 + k * 1024); } while (0)
; #define PG8_LDB(dst, b, h) do { _Pragma("unroll") for (int n = 0; n < 2; ++n) _Pragma("unroll") for (int k = 0; k < 2; ++k) dst[n][k] = *(const PG8_LAS bf16x8*)(lds + PG8_SB(b, h) + boff + n * 2048 + k * 1024); } while (0)
; template <class Epi, class Sched, bool ALIGN_EPI = false, bool SP2 = false>
; __device__ __forceinline__ void gemm_phase(PG8_LAS unsigned char* lds, const Gemm g, const Sched& S, const Epi& E) {
;     ...
;         for (int t = 0; t < nt; t += 2) {
;             const bool last = (t == nt - 2);
;             const char* a1 = cA + (size_t)(t + 1) * kstep;
;             const char* a2 = last ? nA : cA + (size_t)(t + 2) * kstep; const char* b2 = last ? nB : cB + (size_t)(t + 2) * kstep;
;             const char* a3 = a2 + kstep; const char* b3 = b2 + kstep;
;             if (last && has_next) S.a_ready(nxt);
;             if constexpr (SP2) {
;             PG8_LDB(B0, 0, 0); PG8_LDB(B1, 0, 1); PG8_SCHED; PG8_LDA(At, 0, 0); PG8_STAGE(PG8_SA(1, 1), a1 + hstep, voffA);
;             PG8_WAIT_V(8); PG8_WAIT_L(0); PG8_BAR; PG8_MMA(0, 0, At, B0); PG8_MMA(0, 1, At, B1); PG8_BAR; PG8_SCHED;
;             PG8_LDA(At, 0, 1); PG8_STAGE(PG8_SB(0, 0), b2, voffB); PG8_STAGE(PG8_SB(0, 1), b2 + hstep, voffB); PG8_STAGE(PG8_SA(0, 0), a2, voffA);
;             PG8_WAIT_V(8); PG8_WAIT_L(0); PG8_BAR; PG8_MMA(1, 0, At, B0); PG8_MMA(1, 1, At, B1); PG8_BAR; PG8_SCHED;
;             PG8_LDB(B0, 1, 0); PG8_LDB(B1, 1, 1); PG8_SCHED; PG8_LDA(At, 1, 0); PG8_STAGE(PG8_SA(0, 1), a2 + hstep, voffA);
;             PG8_WAIT_V(8); PG8_WAIT_L(0); PG8_BAR; PG8_MMA(0, 0, At, B0); PG8_MMA(0, 1, At, B1); PG8_BAR; PG8_SCHED;
;             PG8_LDA(At, 1, 1); PG8_STAGE(PG8_SB(1, 0), b3, voffB); PG8_STAGE(PG8_SB(1, 1), b3 + hstep, voffB); PG8_STAGE(PG8_SA(1, 0), a3, voffA);
;             PG8_WAIT_V(8); PG8_WAIT_L(0); PG8_BAR; PG8_MMA(1, 0, At, B0); PG8_MMA(1, 1, At, B1); PG8_BAR; PG8_SCHED;
.LBB11_913:
	s_add_u32 s16, s14, 0xfff80080
	s_addc_u32 s17, s15, -1
	s_add_i32 s44, 0, 0x10000
	s_cmp_eq_u32 s43, 28
	s_cselect_b32 s19, s9, s17
	s_cselect_b32 s18, s37, s16
	v_add_u32_e32 v144, s44, v146
	s_cselect_b32 s17, s7, s42
	s_cselect_b32 s16, s40, s41
	s_add_i32 s46, 0, 0x14000
	ds_read_b128 v[150:153], v144
	ds_read_b128 v[154:157], v144 offset:1024
	ds_read_b128 v[158:161], v144 offset:2048
	ds_read_b128 v[162:165], v144 offset:3072
	v_add_u32_e32 v144, s46, v146
	ds_read_b128 v[166:169], v144
	ds_read_b128 v[170:173], v144 offset:1024
	ds_read_b128 v[174:177], v144 offset:2048
	ds_read_b128 v[178:181], v144 offset:3072
	v_lshl_add_u64 v[144:145], s[14:15], 0, v[140:141]
	s_add_i32 m0, s24, 0xc000
	ds_read_b128 v[198:201], v148
	ds_read_b128 v[202:205], v148 offset:1024
	ds_read_b128 v[220:223], v148 offset:2048
	ds_read_b128 v[224:227], v148 offset:3072
	ds_read_b128 v[228:231], v148 offset:4096
	ds_read_b128 v[232:235], v148 offset:5120
	ds_read_b128 v[236:239], v148 offset:6144
	ds_read_b128 v[240:243], v148 offset:7168
	global_load_lds_dwordx4 v[144:145], off
	v_lshl_add_u64 v[144:145], s[14:15], 0, v[142:143]
	s_add_i32 m0, s24, 0xe000
	s_nop 0
	global_load_lds_dwordx4 v[144:145], off
	s_waitcnt vmcnt(8)
	s_waitcnt lgkmcnt(0)
	s_barrier
	s_setprio 1
	s_waitcnt lgkmcnt(0)
	v_mfma_f32_16x16x32_bf16 v[128:131], v[150:153], v[198:201], v[128:131]
	v_mfma_f32_16x16x32_bf16 v[128:131], v[154:157], v[202:205], v[128:131]
	v_mfma_f32_16x16x32_bf16 v[124:127], v[162:165], v[202:205], v[124:127]
	v_mfma_f32_16x16x32_bf16 v[124:127], v[158:161], v[198:201], v[124:127]
	v_mfma_f32_16x16x32_bf16 v[120:123], v[150:153], v[220:223], v[120:123]
	v_mfma_f32_16x16x32_bf16 v[120:123], v[154:157], v[224:227], v[120:123]
	v_mfma_f32_16x16x32_bf16 v[112:115], v[162:165], v[224:227], v[112:115]
	v_mfma_f32_16x16x32_bf16 v[112:115], v[158:161], v[220:223], v[112:115]
	v_mfma_f32_16x16x32_bf16 v[104:107], v[150:153], v[228:231], v[104:107]
	v_mfma_f32_16x16x32_bf16 v[104:107], v[154:157], v[232:235], v[104:107]
	v_mfma_f32_16x16x32_bf16 v[96:99], v[162:165], v[232:235], v[96:99]
	v_mfma_f32_16x16x32_bf16 v[96:99], v[158:161], v[228:231], v[96:99]
	v_mfma_f32_16x16x32_bf16 v[88:91], v[150:153], v[236:239], v[88:91]
	v_mfma_f32_16x16x32_bf16 v[88:91], v[154:157], v[240:243], v[88:91]
	v_mfma_f32_16x16x32_bf16 v[80:83], v[162:165], v[240:243], v[80:83]
	v_mfma_f32_16x16x32_bf16 v[80:83], v[158:161], v[236:239], v[80:83]
	s_setprio 0
	s_setprio 1
	v_mfma_f32_16x16x32_bf16 v[116:119], v[166:169], v[198:201], v[116:119]
	v_mfma_f32_16x16x32_bf16 v[116:119], v[170:173], v[202:205], v[116:119]
	v_mfma_f32_16x16x32_bf16 v[108:111], v[178:181], v[202:205], v[108:111]
	v_mfma_f32_16x16x32_bf16 v[108:111], v[174:177], v[198:201], v[108:111]
	v_mfma_f32_16x16x32_bf16 v[100:103], v[166:169], v[220:223], v[100:103]
	v_mfma_f32_16x16x32_bf16 v[100:103], v[170:173], v[224:227], v[100:103]
	v_mfma_f32_16x16x32_bf16 v[92:95], v[178:181], v[224:227], v[92:95]
	v_mfma_f32_16x16x32_bf16 v[92:95], v[174:177], v[220:223], v[92:95]
	v_mfma_f32_16x16x32_bf16 v[84:87], v[166:169], v[228:231], v[84:87]
	v_mfma_f32_16x16x32_bf16 v[84:87], v[170:173], v[232:235], v[84:87]
	v_mfma_f32_16x16x32_bf16 v[76:79], v[178:181], v[232:235], v[76:79]
	v_mfma_f32_16x16x32_bf16 v[76:79], v[174:177], v[228:231], v[76:79]
	v_mfma_f32_16x16x32_bf16 v[72:75], v[166:169], v[236:239], v[72:75]
	v_mfma_f32_16x16x32_bf16 v[72:75], v[170:173], v[240:243], v[72:75]
	v_mfma_f32_16x16x32_bf16 v[68:71], v[178:181], v[240:243], v[68:71]
	v_mfma_f32_16x16x32_bf16 v[68:71], v[174:177], v[236:239], v[68:71]
	s_setprio 0
	s_barrier
	s_add_i32 s44, s44, s23
	v_lshl_add_u64 v[144:145], s[16:17], 0, v[2:3]
	s_mov_b32 m0, s44
	ds_read_b128 v[198:201], v148 offset:16384
	ds_read_b128 v[202:205], v148 offset:17408
	ds_read_b128 v[220:223], v148 offset:18432
	ds_read_b128 v[224:227], v148 offset:19456
	ds_read_b128 v[228:231], v148 offset:20480
	ds_read_b128 v[232:235], v148 offset:21504
	ds_read_b128 v[236:239], v148 offset:22528
	ds_read_b128 v[240:243], v148 offset:23552
	global_load_lds_dwordx4 v[144:145], off
	s_add_i32 m0, s44, 0x2000
	s_add_u32 s44, s16, 0x80000
	v_lshl_add_u64 v[184:185], s[16:17], 0, v[132:133]
	s_addc_u32 s45, s17, 0
	s_add_i32 s46, s46, s23
	global_load_lds_dwordx4 v[184:185], off
	v_lshl_add_u64 v[186:187], s[44:45], 0, v[2:3]
	s_mov_b32 m0, s46
	v_lshl_add_u64 v[196:197], s[18:19], 0, v[134:135]
	global_load_lds_dwordx4 v[186:187], off
	v_lshl_add_u64 v[186:187], s[44:45], 0, v[132:133]
	s_add_i32 m0, s46, 0x2000
	s_nop 0
	global_load_lds_dwordx4 v[186:187], off
	v_lshl_add_u64 v[186:187], s[18:19], 0, v[136:137]
	s_mov_b32 m0, s24
	s_nop 0
	global_load_lds_dwordx4 v[186:187], off
	s_mov_b32 m0, s25
	s_nop 0
	global_load_lds_dwordx4 v[196:197], off
	s_waitcnt vmcnt(8)
	s_waitcnt lgkmcnt(0)
	s_barrier
; #define PG8_STAGE(bufoff, gbase, voff) do { _Pragma("unroll") for (int _i = 0; _i < 2; ++_i) \
;         __builtin_amdgcn_global_load_lds((const unsigned*)((const char*)(gbase) + (voff)[_i]), (PG8_LAS unsigned*)(lds + (bufoff) + ldsw + _i * 8192), 16, 0, 0); } while (0)
; #define PG8_LDA(dst, b, h) do { _Pragma("unroll") for (int m = 0; m < 4; ++m) _Pragma("unroll") for (int k = 0; k < 2; ++k) dst[m][k] = *(const PG8_LAS bf16x8*)(lds + PG8_SA(b, h) + aoff + m * 2048 + k * 1024); } while (0)
; #define PG8_LDB(dst, b, h) do { _Pragma("unroll") for (int n = 0; n < 2; ++n) _Pragma("unroll") for (int k = 0; k < 2; ++k) dst[n][k] = *(const PG8_LAS bf16x8*)(lds + PG8_SB(b, h) + boff + n * 2048 + k * 1024); } while (0)
; #define PG8_MMA(ai, bj, At, Bt) do { __builtin_amdgcn_s_setprio(1); _Pragma("unroll") for (int m = 0; m < 4; ++m) _Pragma("unroll") for (int n = 0; n < 2; ++n) _Pragma("unroll") for (int k = 0; k < 2; ++k) \
;         acc[ai][bj][m][n] = __builtin_amdgcn_mfma_f32_16x16x32_bf16(Bt[n][k], At[m][k], acc[ai][bj][m][n], 0, 0, 0); __builtin_amdgcn_s_setprio(0); } while (0)
; #define PG8_WAIT_V(n) asm volatile("s_waitcnt vmcnt(" #n ")" ::: "memory")
; #define PG8_WAIT_L(n) asm volatile("s_waitcnt lgkmcnt(" #n ")" ::: "memory")
; #define PG8_BAR __builtin_amdgcn_s_barrier()
; #define PG8_SCHED __builtin_amdgcn_sched_barrier(0)
; template <class Epi, class Sched, bool ALIGN_EPI = false, bool SP2 = false>
; __device__ __forceinline__ void gemm_phase(PG8_LAS unsigned char* lds, const Gemm g, const Sched& S, const Epi& E) {
;     ...
;             PG8_LDB(B0, 0, 0); PG8_LDB(B1, 0, 1); PG8_SCHED; PG8_LDA(At, 0, 0); PG8_STAGE(PG8_SA(1, 1), a1 + hstep, voffA);
;             PG8_WAIT_V(8); PG8_WAIT_L(0); PG8_BAR; PG8_MMA(0, 0, At, B0); PG8_MMA(0, 1, At, B1); PG8_BAR; PG8_SCHED;
;             PG8_LDA(At, 0, 1); PG8_STAGE(PG8_SB(0, 0), b2, voffB); PG8_STAGE(PG8_SB(0, 1), b2 + hstep, voffB); PG8_STAGE(PG8_SA(0, 0), a2, voffA);
;             PG8_WAIT_V(8); PG8_WAIT_L(0); PG8_BAR; PG8_MMA(1, 0, At, B0); PG8_MMA(1, 1, At, B1); PG8_BAR; PG8_SCHED;
;             PG8_LDB(B0, 1, 0); PG8_LDB(B1, 1, 1); PG8_SCHED; PG8_LDA(At, 1, 0); PG8_STAGE(PG8_SA(0, 1), a2 + hstep, voffA);
;             PG8_WAIT_V(8); PG8_WAIT_L(0); PG8_BAR; PG8_MMA(0, 0, At, B0); PG8_MMA(0, 1, At, B1); PG8_BAR; PG8_SCHED;
	s_setprio 1
	s_waitcnt lgkmcnt(0)
	v_mfma_f32_16x16x32_bf16 v[64:67], v[150:153], v[198:201], v[64:67]
	v_mfma_f32_16x16x32_bf16 v[64:67], v[154:157], v[202:205], v[64:67]
	v_mfma_f32_16x16x32_bf16 v[60:63], v[162:165], v[202:205], v[60:63]
	v_mfma_f32_16x16x32_bf16 v[60:63], v[158:161], v[198:201], v[60:63]
	v_mfma_f32_16x16x32_bf16 v[56:59], v[150:153], v[220:223], v[56:59]
	v_mfma_f32_16x16x32_bf16 v[56:59], v[154:157], v[224:227], v[56:59]
	v_mfma_f32_16x16x32_bf16 v[48:51], v[162:165], v[224:227], v[48:51]
	v_mfma_f32_16x16x32_bf16 v[48:51], v[158:161], v[220:223], v[48:51]
	v_mfma_f32_16x16x32_bf16 v[40:43], v[150:153], v[228:231], v[40:43]
	v_mfma_f32_16x16x32_bf16 v[40:43], v[154:157], v[232:235], v[40:43]
	v_mfma_f32_16x16x32_bf16 v[32:35], v[162:165], v[232:235], v[32:35]
	v_mfma_f32_16x16x32_bf16 v[32:35], v[158:161], v[228:231], v[32:35]
	v_mfma_f32_16x16x32_bf16 v[24:27], v[150:153], v[236:239], v[24:27]
	v_mfma_f32_16x16x32_bf16 v[24:27], v[154:157], v[240:243], v[24:27]
	v_mfma_f32_16x16x32_bf16 v[16:19], v[162:165], v[240:243], v[16:19]
	v_mfma_f32_16x16x32_bf16 v[16:19], v[158:161], v[236:239], v[16:19]
	s_setprio 0
	s_setprio 1
	v_mfma_f32_16x16x32_bf16 v[52:55], v[166:169], v[198:201], v[52:55]
	v_mfma_f32_16x16x32_bf16 v[52:55], v[170:173], v[202:205], v[52:55]
	v_mfma_f32_16x16x32_bf16 v[44:47], v[178:181], v[202:205], v[44:47]
	v_mfma_f32_16x16x32_bf16 v[44:47], v[174:177], v[198:201], v[44:47]
	v_mfma_f32_16x16x32_bf16 v[36:39], v[166:169], v[220:223], v[36:39]
	v_mfma_f32_16x16x32_bf16 v[36:39], v[170:173], v[224:227], v[36:39]
	v_mfma_f32_16x16x32_bf16 v[28:31], v[178:181], v[224:227], v[28:31]
	v_mfma_f32_16x16x32_bf16 v[28:31], v[174:177], v[220:223], v[28:31]
	v_mfma_f32_16x16x32_bf16 v[20:23], v[166:169], v[228:231], v[20:23]
	v_mfma_f32_16x16x32_bf16 v[20:23], v[170:173], v[232:235], v[20:23]
	v_mfma_f32_16x16x32_bf16 v[12:15], v[178:181], v[232:235], v[12:15]
	v_mfma_f32_16x16x32_bf16 v[12:15], v[174:177], v[228:231], v[12:15]
	v_mfma_f32_16x16x32_bf16 v[8:11], v[166:169], v[236:239], v[8:11]
	v_mfma_f32_16x16x32_bf16 v[8:11], v[170:173], v[240:243], v[8:11]
	v_mfma_f32_16x16x32_bf16 v[4:7], v[178:181], v[240:243], v[4:7]
	v_mfma_f32_16x16x32_bf16 v[4:7], v[174:177], v[236:239], v[4:7]
	s_setprio 0
	s_barrier
	s_add_i32 s44, 0, 0x18000
	v_add_u32_e32 v149, s44, v146
	s_add_i32 s45, 0, 0x1c000
	ds_read_b128 v[150:153], v149
	ds_read_b128 v[154:157], v149 offset:1024
	ds_read_b128 v[158:161], v149 offset:2048
	ds_read_b128 v[162:165], v149 offset:3072
	v_add_u32_e32 v149, s45, v146
	ds_read_b128 v[166:169], v149
	ds_read_b128 v[170:173], v149 offset:1024
	ds_read_b128 v[174:177], v149 offset:2048
	ds_read_b128 v[178:181], v149 offset:3072
	s_add_u32 s18, s18, 0x80000
	s_addc_u32 s19, s19, 0
	s_mov_b32 m0, s26
	v_lshl_add_u64 v[206:207], s[18:19], 0, v[136:137]
	ds_read_b128 v[198:201], v148 offset:32768
	ds_read_b128 v[202:205], v148 offset:33792
	ds_read_b128 v[220:223], v148 offset:34816
	ds_read_b128 v[224:227], v148 offset:35840
	ds_read_b128 v[228:231], v148 offset:36864
	ds_read_b128 v[232:235], v148 offset:37888
	ds_read_b128 v[236:239], v148 offset:38912
	ds_read_b128 v[240:243], v148 offset:39936
	global_load_lds_dwordx4 v[206:207], off
	v_lshl_add_u64 v[206:207], s[18:19], 0, v[134:135]
	s_mov_b32 m0, s27
	s_nop 0
	global_load_lds_dwordx4 v[206:207], off
	s_waitcnt vmcnt(8)
	s_waitcnt lgkmcnt(0)
	s_barrier
	s_setprio 1
	s_waitcnt lgkmcnt(0)
	v_mfma_f32_16x16x32_bf16 v[128:131], v[150:153], v[198:201], v[128:131]
	v_mfma_f32_16x16x32_bf16 v[128:131], v[154:157], v[202:205], v[128:131]
	v_mfma_f32_16x16x32_bf16 v[124:127], v[162:165], v[202:205], v[124:127]
	v_mfma_f32_16x16x32_bf16 v[124:127], v[158:161], v[198:201], v[124:127]
	v_mfma_f32_16x16x32_bf16 v[120:123], v[150:153], v[220:223], v[120:123]
	v_mfma_f32_16x16x32_bf16 v[120:123], v[154:157], v[224:227], v[120:123]
	v_mfma_f32_16x16x32_bf16 v[112:115], v[162:165], v[224:227], v[112:115]
	v_mfma_f32_16x16x32_bf16 v[112:115], v[158:161], v[220:223], v[112:115]
	v_mfma_f32_16x16x32_bf16 v[104:107], v[150:153], v[228:231], v[104:107]
	v_mfma_f32_16x16x32_bf16 v[104:107], v[154:157], v[232:235], v[104:107]
	v_mfma_f32_16x16x32_bf16 v[96:99], v[162:165], v[232:235], v[96:99]
	v_mfma_f32_16x16x32_bf16 v[96:99], v[158:161], v[228:231], v[96:99]
	v_mfma_f32_16x16x32_bf16 v[88:91], v[150:153], v[236:239], v[88:91]
	v_mfma_f32_16x16x32_bf16 v[88:91], v[154:157], v[240:243], v[88:91]
	v_mfma_f32_16x16x32_bf16 v[80:83], v[162:165], v[240:243], v[80:83]
	v_mfma_f32_16x16x32_bf16 v[80:83], v[158:161], v[236:239], v[80:83]
	s_setprio 0
	s_setprio 1
	v_mfma_f32_16x16x32_bf16 v[116:119], v[166:169], v[198:201], v[116:119]
	v_mfma_f32_16x16x32_bf16 v[116:119], v[170:173], v[202:205], v[116:119]
	v_mfma_f32_16x16x32_bf16 v[108:111], v[178:181], v[202:205], v[108:111]
	v_mfma_f32_16x16x32_bf16 v[108:111], v[174:177], v[198:201], v[108:111]
	v_mfma_f32_16x16x32_bf16 v[100:103], v[166:169], v[220:223], v[100:103]
	v_mfma_f32_16x16x32_bf16 v[100:103], v[170:173], v[224:227], v[100:103]
	v_mfma_f32_16x16x32_bf16 v[92:95], v[178:181], v[224:227], v[92:95]
	v_mfma_f32_16x16x32_bf16 v[92:95], v[174:177], v[220:223], v[92:95]
	v_mfma_f32_16x16x32_bf16 v[84:87], v[166:169], v[228:231], v[84:87]
	v_mfma_f32_16x16x32_bf16 v[84:87], v[170:173], v[232:235], v[84:87]
	v_mfma_f32_16x16x32_bf16 v[76:79], v[178:181], v[232:235], v[76:79]
	v_mfma_f32_16x16x32_bf16 v[76:79], v[174:177], v[228:231], v[76:79]
	v_mfma_f32_16x16x32_bf16 v[72:75], v[166:169], v[236:239], v[72:75]
	v_mfma_f32_16x16x32_bf16 v[72:75], v[170:173], v[240:243], v[72:75]
	v_mfma_f32_16x16x32_bf16 v[68:71], v[178:181], v[240:243], v[68:71]
	v_mfma_f32_16x16x32_bf16 v[68:71], v[174:177], v[236:239], v[68:71]
	s_setprio 0
	s_barrier
; #define PG8_STAGE(bufoff, gbase, voff) do { _Pragma("unroll") for (int _i = 0; _i < 2; ++_i) \
;         __builtin_amdgcn_global_load_lds((const unsigned*)((const char*)(gbase) + (voff)[_i]), (PG8_LAS unsigned*)(lds + (bufoff) + ldsw + _i * 8192), 16, 0, 0); } while (0)
; #define PG8_LDA(dst, b, h) do { _Pragma("unroll") for (int m = 0; m < 4; ++m) _Pragma("unroll") for (int k = 0; k < 2; ++k) dst[m][k] = *(const PG8_LAS bf16x8*)(lds + PG8_SA(b, h) + aoff + m * 2048 + k * 1024); } while (0)
; #define PG8_MMA(ai, bj, At, Bt) do { __builtin_amdgcn_s_setprio(1); _Pragma("unroll") for (int m = 0; m < 4; ++m) _Pragma("unroll") for (int n = 0; n < 2; ++n) _Pragma("unroll") for (int k = 0; k < 2; ++k) \
;         acc[ai][bj][m][n] = __builtin_amdgcn_mfma_f32_16x16x32_bf16(Bt[n][k], At[m][k], acc[ai][bj][m][n], 0, 0, 0); __builtin_amdgcn_s_setprio(0); } while (0)
; #define PG8_WAIT_V(n) asm volatile("s_waitcnt vmcnt(" #n ")" ::: "memory")
; #define PG8_WAIT_L(n) asm volatile("s_waitcnt lgkmcnt(" #n ")" ::: "memory")
; #define PG8_BAR __builtin_amdgcn_s_barrier()
; #define PG8_SCHED __builtin_amdgcn_sched_barrier(0)
; template <class Epi, class Sched, bool ALIGN_EPI = false, bool SP2 = false>
; __device__ __forceinline__ void gemm_phase(PG8_LAS unsigned char* lds, const Gemm g, const Sched& S, const Epi& E) {
;     ...
;             PG8_WAIT_V(8); PG8_WAIT_L(0); PG8_BAR; PG8_MMA(0, 0, At, B0); PG8_MMA(0, 1, At, B1); PG8_BAR; PG8_SCHED;
;             PG8_LDA(At, 1, 1); PG8_STAGE(PG8_SB(1, 0), b3, voffB); PG8_STAGE(PG8_SB(1, 1), b3 + hstep, voffB); PG8_STAGE(PG8_SA(1, 0), a3, voffA);
;             PG8_WAIT_V(8); PG8_WAIT_L(0); PG8_BAR; PG8_MMA(1, 0, At, B0); PG8_MMA(1, 1, At, B1); PG8_BAR; PG8_SCHED;
	s_add_i32 s18, s44, s23
	v_lshl_add_u64 v[144:145], v[144:145], 0, s[34:35]
	s_mov_b32 m0, s18
	ds_read_b128 v[198:201], v148 offset:49152
	ds_read_b128 v[202:205], v148 offset:50176
	ds_read_b128 v[220:223], v148 offset:51200
	ds_read_b128 v[224:227], v148 offset:52224
	ds_read_b128 v[228:231], v148 offset:53248
	ds_read_b128 v[232:235], v148 offset:54272
	ds_read_b128 v[236:239], v148 offset:55296
	ds_read_b128 v[240:243], v148 offset:56320
	global_load_lds_dwordx4 v[144:145], off
	s_add_i32 m0, s18, 0x2000
	s_add_u32 s16, s16, 0x80080
	v_lshl_add_u64 v[144:145], v[184:185], 0, s[34:35]
	s_addc_u32 s17, s17, 0
	s_add_i32 s18, s45, s23
	global_load_lds_dwordx4 v[144:145], off
	v_lshl_add_u64 v[144:145], s[16:17], 0, v[2:3]
	s_mov_b32 m0, s18
	s_nop 0
	global_load_lds_dwordx4 v[144:145], off
	v_lshl_add_u64 v[144:145], s[16:17], 0, v[132:133]
	s_add_i32 m0, s18, 0x2000
	s_nop 0
	global_load_lds_dwordx4 v[144:145], off
	v_lshl_add_u64 v[144:145], v[186:187], 0, s[34:35]
	s_mov_b32 m0, s28
	s_nop 0
	global_load_lds_dwordx4 v[144:145], off
	v_lshl_add_u64 v[144:145], v[196:197], 0, s[34:35]
	s_mov_b32 m0, s29
	s_nop 0
	global_load_lds_dwordx4 v[144:145], off
	s_waitcnt vmcnt(8)
	s_waitcnt lgkmcnt(0)
	s_barrier
	s_setprio 1
	s_waitcnt lgkmcnt(0)
	v_mfma_f32_16x16x32_bf16 v[64:67], v[150:153], v[198:201], v[64:67]
	v_mfma_f32_16x16x32_bf16 v[64:67], v[154:157], v[202:205], v[64:67]
	v_mfma_f32_16x16x32_bf16 v[60:63], v[162:165], v[202:205], v[60:63]
	v_mfma_f32_16x16x32_bf16 v[60:63], v[158:161], v[198:201], v[60:63]
	v_mfma_f32_16x16x32_bf16 v[56:59], v[150:153], v[220:223], v[56:59]
	v_mfma_f32_16x16x32_bf16 v[56:59], v[154:157], v[224:227], v[56:59]
	v_mfma_f32_16x16x32_bf16 v[48:51], v[162:165], v[224:227], v[48:51]
	v_mfma_f32_16x16x32_bf16 v[48:51], v[158:161], v[220:223], v[48:51]
	v_mfma_f32_16x16x32_bf16 v[40:43], v[150:153], v[228:231], v[40:43]
	v_mfma_f32_16x16x32_bf16 v[40:43], v[154:157], v[232:235], v[40:43]
	v_mfma_f32_16x16x32_bf16 v[32:35], v[162:165], v[232:235], v[32:35]
	v_mfma_f32_16x16x32_bf16 v[32:35], v[158:161], v[228:231], v[32:35]
	v_mfma_f32_16x16x32_bf16 v[24:27], v[150:153], v[236:239], v[24:27]
	v_mfma_f32_16x16x32_bf16 v[24:27], v[154:157], v[240:243], v[24:27]
	v_mfma_f32_16x16x32_bf16 v[16:19], v[162:165], v[240:243], v[16:19]
	v_mfma_f32_16x16x32_bf16 v[16:19], v[158:161], v[236:239], v[16:19]
	s_setprio 0
	s_setprio 1
	v_mfma_f32_16x16x32_bf16 v[52:55], v[166:169], v[198:201], v[52:55]
	v_mfma_f32_16x16x32_bf16 v[52:55], v[170:173], v[202:205], v[52:55]
	v_mfma_f32_16x16x32_bf16 v[44:47], v[178:181], v[202:205], v[44:47]
	v_mfma_f32_16x16x32_bf16 v[44:47], v[174:177], v[198:201], v[44:47]
	v_mfma_f32_16x16x32_bf16 v[36:39], v[166:169], v[220:223], v[36:39]
	v_mfma_f32_16x16x32_bf16 v[36:39], v[170:173], v[224:227], v[36:39]
	v_mfma_f32_16x16x32_bf16 v[28:31], v[178:181], v[224:227], v[28:31]
	v_mfma_f32_16x16x32_bf16 v[28:31], v[174:177], v[220:223], v[28:31]
	v_mfma_f32_16x16x32_bf16 v[20:23], v[166:169], v[228:231], v[20:23]
	v_mfma_f32_16x16x32_bf16 v[20:23], v[170:173], v[232:235], v[20:23]
	v_mfma_f32_16x16x32_bf16 v[12:15], v[178:181], v[232:235], v[12:15]
	v_mfma_f32_16x16x32_bf16 v[12:15], v[174:177], v[228:231], v[12:15]
	v_mfma_f32_16x16x32_bf16 v[8:11], v[166:169], v[236:239], v[8:11]
	v_mfma_f32_16x16x32_bf16 v[8:11], v[170:173], v[240:243], v[8:11]
	v_mfma_f32_16x16x32_bf16 v[4:7], v[178:181], v[240:243], v[4:7]
	v_mfma_f32_16x16x32_bf16 v[4:7], v[174:177], v[236:239], v[4:7]
	s_setprio 0
	s_barrier
	s_add_i32 s43, s43, 2
	s_add_u32 s14, s14, 0x100
	s_addc_u32 s15, s15, 0
	s_add_u32 s41, s41, 0x100
	s_addc_u32 s42, s42, 0
	s_cmp_gt_u32 s43, 29
	s_cbranch_scc0 .LBB11_913
	s_and_b64 vcc, exec, s[4:5]
	s_cbranch_vccz .LBB11_916
	s_barrier

; #define PG8_STAGE(bufoff, gbase, voff) do { _Pragma("unroll") for (int _i = 0; _i < 2; ++_i) \
;         __builtin_amdgcn_global_load_lds((const unsigned*)((const char*)(gbase) + (voff)[_i]), (PG8_LAS unsigned*)(lds + (bufoff) + ldsw + _i * 8192), 16, 0, 0); } while (0)
; #define PG8_LDA(dst, b, h) do { _Pragma("unroll") for (int m = 0; m < 4; ++m) _Pragma("unroll") for (int k = 0; k < 2; ++k) dst[m][k] = *(const PG8_LAS bf16x8*)(lds + PG8_SA(b, h) + aoff + m * 2048 + k * 1024); } while (0)
; #define PG8_LDB(dst, b, h) do { _Pragma("unroll") for (int n = 0; n < 2; ++n) _Pragma("unroll") for (int k = 0; k < 2; ++k) dst[n][k] = *(const PG8_LAS bf16x8*)(lds + PG8_SB(b, h) + boff + n * 2048 + k * 1024); } while (0)
; template <class Epi, class Sched, bool ALIGN_EPI = false, bool SP2 = false>
; __device__ __forceinline__ void gemm_phase(PG8_LAS unsigned char* lds, const Gemm g, const Sched& S, const Epi& E) {
;     ...
;         for (int t = 0; t < nt; t += 2) {
;             const bool last = (t == nt - 2);
;             const char* a1 = cA + (size_t)(t + 1) * kstep;
;             const char* a2 = last ? nA : cA + (size_t)(t + 2) * kstep; const char* b2 = last ? nB : cB + (size_t)(t + 2) * kstep;
;             const char* a3 = a2 + kstep; const char* b3 = b2 + kstep;
;             if (last && has_next) S.a_ready(nxt);
;             if constexpr (SP2) {
;             PG8_LDB(B0, 0, 0); PG8_LDB(B1, 0, 1); PG8_SCHED; PG8_LDA(At, 0, 0); PG8_STAGE(PG8_SA(1, 1), a1 + hstep, voffA);
;             PG8_WAIT_V(8); PG8_WAIT_L(0); PG8_BAR; PG8_MMA(0, 0, At, B0); PG8_MMA(0, 1, At, B1); PG8_BAR; PG8_SCHED;
;             PG8_LDA(At, 0, 1); PG8_STAGE(PG8_SB(0, 0), b2, voffB); PG8_STAGE(PG8_SB(0, 1), b2 + hstep, voffB); PG8_STAGE(PG8_SA(0, 0), a2, voffA);
;             PG8_WAIT_V(8); PG8_WAIT_L(0); PG8_BAR; PG8_MMA(1, 0, At, B0); PG8_MMA(1, 1, At, B1); PG8_BAR; PG8_SCHED;
;             PG8_LDB(B0, 1, 0); PG8_LDB(B1, 1, 1); PG8_SCHED; PG8_LDA(At, 1, 0); PG8_STAGE(PG8_SA(0, 1), a2 + hstep, voffA);
;             PG8_WAIT_V(8); PG8_WAIT_L(0); PG8_BAR; PG8_MMA(0, 0, At, B0); PG8_MMA(0, 1, At, B1); PG8_BAR; PG8_SCHED;
;             PG8_LDA(At, 1, 1); PG8_STAGE(PG8_SB(1, 0), b3, voffB); PG8_STAGE(PG8_SB(1, 1), b3 + hstep, voffB); PG8_STAGE(PG8_SA(1, 0), a3, voffA);
;             PG8_WAIT_V(8); PG8_WAIT_L(0); PG8_BAR; PG8_MMA(1, 0, At, B0); PG8_MMA(1, 1, At, B1); PG8_BAR; PG8_SCHED;
.LBB11_1071:
	s_add_u32 s16, s14, 0xfff80080
	s_addc_u32 s17, s15, -1
	s_add_i32 s46, 0, 0x10000
	s_cmp_eq_u32 s45, 28
	s_cselect_b32 s19, s9, s17
	s_cselect_b32 s18, s41, s16
	v_add_u32_e32 v2, s46, v168
	s_cselect_b32 s17, s7, s44
	s_cselect_b32 s16, s42, s43
	s_add_i32 s48, 0, 0x14000
	ds_read_b128 v[132:135], v2
	ds_read_b128 v[136:139], v2 offset:1024
	ds_read_b128 v[140:143], v2 offset:2048
	ds_read_b128 v[144:147], v2 offset:3072
	v_add_u32_e32 v2, s48, v168
	ds_read_b128 v[170:173], v2
	ds_read_b128 v[174:177], v2 offset:1024
	ds_read_b128 v[178:181], v2 offset:2048
	ds_read_b128 v[198:201], v2 offset:3072
	v_lshl_add_u64 v[166:167], s[14:15], 0, v[162:163]
	s_add_i32 m0, s25, 0xc000
	ds_read_b128 v[202:205], v169
	ds_read_b128 v[220:223], v169 offset:1024
	ds_read_b128 v[224:227], v169 offset:2048
	ds_read_b128 v[228:231], v169 offset:3072
	ds_read_b128 v[232:235], v169 offset:4096
	ds_read_b128 v[236:239], v169 offset:5120
	ds_read_b128 v[240:243], v169 offset:6144
	ds_read_b128 v[244:247], v169 offset:7168
	global_load_lds_dwordx4 v[166:167], off
	v_lshl_add_u64 v[166:167], s[14:15], 0, v[164:165]
	s_add_i32 m0, s25, 0xe000
	s_nop 0
	global_load_lds_dwordx4 v[166:167], off
	s_waitcnt vmcnt(8)
	s_waitcnt lgkmcnt(0)
	s_barrier
	s_setprio 1
	s_waitcnt lgkmcnt(0)
	v_mfma_f32_16x16x32_bf16 v[128:131], v[132:135], v[202:205], v[128:131]
	v_mfma_f32_16x16x32_bf16 v[128:131], v[136:139], v[220:223], v[128:131]
	v_mfma_f32_16x16x32_bf16 v[124:127], v[144:147], v[220:223], v[124:127]
	v_mfma_f32_16x16x32_bf16 v[124:127], v[140:143], v[202:205], v[124:127]
	v_mfma_f32_16x16x32_bf16 v[120:123], v[132:135], v[224:227], v[120:123]
	v_mfma_f32_16x16x32_bf16 v[120:123], v[136:139], v[228:231], v[120:123]
	v_mfma_f32_16x16x32_bf16 v[112:115], v[144:147], v[228:231], v[112:115]
	v_mfma_f32_16x16x32_bf16 v[112:115], v[140:143], v[224:227], v[112:115]
	v_mfma_f32_16x16x32_bf16 v[104:107], v[132:135], v[232:235], v[104:107]
	v_mfma_f32_16x16x32_bf16 v[104:107], v[136:139], v[236:239], v[104:107]
	v_mfma_f32_16x16x32_bf16 v[96:99], v[144:147], v[236:239], v[96:99]
	v_mfma_f32_16x16x32_bf16 v[96:99], v[140:143], v[232:235], v[96:99]
	v_mfma_f32_16x16x32_bf16 v[88:91], v[132:135], v[240:243], v[88:91]
	v_mfma_f32_16x16x32_bf16 v[88:91], v[136:139], v[244:247], v[88:91]
	v_mfma_f32_16x16x32_bf16 v[80:83], v[144:147], v[244:247], v[80:83]
	v_mfma_f32_16x16x32_bf16 v[80:83], v[140:143], v[240:243], v[80:83]
	s_setprio 0
	s_setprio 1
	v_mfma_f32_16x16x32_bf16 v[116:119], v[170:173], v[202:205], v[116:119]
	v_mfma_f32_16x16x32_bf16 v[116:119], v[174:177], v[220:223], v[116:119]
	v_mfma_f32_16x16x32_bf16 v[108:111], v[198:201], v[220:223], v[108:111]
	v_mfma_f32_16x16x32_bf16 v[108:111], v[178:181], v[202:205], v[108:111]
	v_mfma_f32_16x16x32_bf16 v[100:103], v[170:173], v[224:227], v[100:103]
	v_mfma_f32_16x16x32_bf16 v[100:103], v[174:177], v[228:231], v[100:103]
	v_mfma_f32_16x16x32_bf16 v[92:95], v[198:201], v[228:231], v[92:95]
	v_mfma_f32_16x16x32_bf16 v[92:95], v[178:181], v[224:227], v[92:95]
	v_mfma_f32_16x16x32_bf16 v[84:87], v[170:173], v[232:235], v[84:87]
	v_mfma_f32_16x16x32_bf16 v[84:87], v[174:177], v[236:239], v[84:87]
	v_mfma_f32_16x16x32_bf16 v[76:79], v[198:201], v[236:239], v[76:79]
	v_mfma_f32_16x16x32_bf16 v[76:79], v[178:181], v[232:235], v[76:79]
	v_mfma_f32_16x16x32_bf16 v[72:75], v[170:173], v[240:243], v[72:75]
	v_mfma_f32_16x16x32_bf16 v[72:75], v[174:177], v[244:247], v[72:75]
	v_mfma_f32_16x16x32_bf16 v[68:71], v[198:201], v[244:247], v[68:71]
	v_mfma_f32_16x16x32_bf16 v[68:71], v[178:181], v[240:243], v[68:71]
	s_setprio 0
	s_barrier
	s_add_i32 s46, s46, s24
	v_lshl_add_u64 v[166:167], s[16:17], 0, v[154:155]
	s_mov_b32 m0, s46
	ds_read_b128 v[202:205], v169 offset:16384
	ds_read_b128 v[220:223], v169 offset:17408
	ds_read_b128 v[224:227], v169 offset:18432
	ds_read_b128 v[228:231], v169 offset:19456
	ds_read_b128 v[232:235], v169 offset:20480
	ds_read_b128 v[236:239], v169 offset:21504
	ds_read_b128 v[240:243], v169 offset:22528
	ds_read_b128 v[244:247], v169 offset:23552
	global_load_lds_dwordx4 v[166:167], off
	s_add_i32 m0, s46, 0x2000
	s_add_u32 s46, s16, 0x80000
	v_lshl_add_u64 v[196:197], s[16:17], 0, v[150:151]
	s_addc_u32 s47, s17, 0
	s_add_i32 s48, s48, s24
	global_load_lds_dwordx4 v[196:197], off
	v_lshl_add_u64 v[206:207], s[46:47], 0, v[154:155]
	s_mov_b32 m0, s48
	v_lshl_add_u64 v[184:185], s[18:19], 0, v[152:153]
	global_load_lds_dwordx4 v[206:207], off
	v_lshl_add_u64 v[206:207], s[46:47], 0, v[150:151]
	s_add_i32 m0, s48, 0x2000
	s_nop 0
	global_load_lds_dwordx4 v[206:207], off
	v_lshl_add_u64 v[206:207], s[18:19], 0, v[156:157]
	s_mov_b32 m0, s25
	s_nop 0
	global_load_lds_dwordx4 v[206:207], off
	s_mov_b32 m0, s26
	s_nop 0
	global_load_lds_dwordx4 v[184:185], off
	s_waitcnt vmcnt(8)
	s_waitcnt lgkmcnt(0)
	s_barrier
; #define PG8_STAGE(bufoff, gbase, voff) do { _Pragma("unroll") for (int _i = 0; _i < 2; ++_i) \
;         __builtin_amdgcn_global_load_lds((const unsigned*)((const char*)(gbase) + (voff)[_i]), (PG8_LAS unsigned*)(lds + (bufoff) + ldsw + _i * 8192), 16, 0, 0); } while (0)
; #define PG8_LDA(dst, b, h) do { _Pragma("unroll") for (int m = 0; m < 4; ++m) _Pragma("unroll") for (int k = 0; k < 2; ++k) dst[m][k] = *(const PG8_LAS bf16x8*)(lds + PG8_SA(b, h) + aoff + m * 2048 + k * 1024); } while (0)
; #define PG8_LDB(dst, b, h) do { _Pragma("unroll") for (int n = 0; n < 2; ++n) _Pragma("unroll") for (int k = 0; k < 2; ++k) dst[n][k] = *(const PG8_LAS bf16x8*)(lds + PG8_SB(b, h) + boff + n * 2048 + k * 1024); } while (0)
; #define PG8_MMA(ai, bj, At, Bt) do { __builtin_amdgcn_s_setprio(1); _Pragma("unroll") for (int m = 0; m < 4; ++m) _Pragma("unroll") for (int n = 0; n < 2; ++n) _Pragma("unroll") for (int k = 0; k < 2; ++k) \
;         acc[ai][bj][m][n] = __builtin_amdgcn_mfma_f32_16x16x32_bf16(Bt[n][k], At[m][k], acc[ai][bj][m][n], 0, 0, 0); __builtin_amdgcn_s_setprio(0); } while (0)
; #define PG8_WAIT_V(n) asm volatile("s_waitcnt vmcnt(" #n ")" ::: "memory")
; #define PG8_WAIT_L(n) asm volatile("s_waitcnt lgkmcnt(" #n ")" ::: "memory")
; #define PG8_BAR __builtin_amdgcn_s_barrier()
; #define PG8_SCHED __builtin_amdgcn_sched_barrier(0)
; template <class Epi, class Sched, bool ALIGN_EPI = false, bool SP2 = false>
; __device__ __forceinline__ void gemm_phase(PG8_LAS unsigned char* lds, const Gemm g, const Sched& S, const Epi& E) {
;     ...
;             PG8_LDB(B0, 0, 0); PG8_LDB(B1, 0, 1); PG8_SCHED; PG8_LDA(At, 0, 0); PG8_STAGE(PG8_SA(1, 1), a1 + hstep, voffA);
;             PG8_WAIT_V(8); PG8_WAIT_L(0); PG8_BAR; PG8_MMA(0, 0, At, B0); PG8_MMA(0, 1, At, B1); PG8_BAR; PG8_SCHED;
;             PG8_LDA(At, 0, 1); PG8_STAGE(PG8_SB(0, 0), b2, voffB); PG8_STAGE(PG8_SB(0, 1), b2 + hstep, voffB); PG8_STAGE(PG8_SA(0, 0), a2, voffA);
;             PG8_WAIT_V(8); PG8_WAIT_L(0); PG8_BAR; PG8_MMA(1, 0, At, B0); PG8_MMA(1, 1, At, B1); PG8_BAR; PG8_SCHED;
;             PG8_LDB(B0, 1, 0); PG8_LDB(B1, 1, 1); PG8_SCHED; PG8_LDA(At, 1, 0); PG8_STAGE(PG8_SA(0, 1), a2 + hstep, voffA);
;             PG8_WAIT_V(8); PG8_WAIT_L(0); PG8_BAR; PG8_MMA(0, 0, At, B0); PG8_MMA(0, 1, At, B1); PG8_BAR; PG8_SCHED;
	s_setprio 1
	s_waitcnt lgkmcnt(0)
	v_mfma_f32_16x16x32_bf16 v[64:67], v[132:135], v[202:205], v[64:67]
	v_mfma_f32_16x16x32_bf16 v[64:67], v[136:139], v[220:223], v[64:67]
	v_mfma_f32_16x16x32_bf16 v[60:63], v[144:147], v[220:223], v[60:63]
	v_mfma_f32_16x16x32_bf16 v[60:63], v[140:143], v[202:205], v[60:63]
	v_mfma_f32_16x16x32_bf16 v[56:59], v[132:135], v[224:227], v[56:59]
	v_mfma_f32_16x16x32_bf16 v[56:59], v[136:139], v[228:231], v[56:59]
	v_mfma_f32_16x16x32_bf16 v[48:51], v[144:147], v[228:231], v[48:51]
	v_mfma_f32_16x16x32_bf16 v[48:51], v[140:143], v[224:227], v[48:51]
	v_mfma_f32_16x16x32_bf16 v[40:43], v[132:135], v[232:235], v[40:43]
	v_mfma_f32_16x16x32_bf16 v[40:43], v[136:139], v[236:239], v[40:43]
	v_mfma_f32_16x16x32_bf16 v[32:35], v[144:147], v[236:239], v[32:35]
	v_mfma_f32_16x16x32_bf16 v[32:35], v[140:143], v[232:235], v[32:35]
	v_mfma_f32_16x16x32_bf16 v[24:27], v[132:135], v[240:243], v[24:27]
	v_mfma_f32_16x16x32_bf16 v[24:27], v[136:139], v[244:247], v[24:27]
	v_mfma_f32_16x16x32_bf16 v[16:19], v[144:147], v[244:247], v[16:19]
	v_mfma_f32_16x16x32_bf16 v[16:19], v[140:143], v[240:243], v[16:19]
	s_setprio 0
	s_setprio 1
	v_mfma_f32_16x16x32_bf16 v[52:55], v[170:173], v[202:205], v[52:55]
	v_mfma_f32_16x16x32_bf16 v[52:55], v[174:177], v[220:223], v[52:55]
	v_mfma_f32_16x16x32_bf16 v[44:47], v[198:201], v[220:223], v[44:47]
	v_mfma_f32_16x16x32_bf16 v[44:47], v[178:181], v[202:205], v[44:47]
	v_mfma_f32_16x16x32_bf16 v[36:39], v[170:173], v[224:227], v[36:39]
	v_mfma_f32_16x16x32_bf16 v[36:39], v[174:177], v[228:231], v[36:39]
	v_mfma_f32_16x16x32_bf16 v[28:31], v[198:201], v[228:231], v[28:31]
	v_mfma_f32_16x16x32_bf16 v[28:31], v[178:181], v[224:227], v[28:31]
	v_mfma_f32_16x16x32_bf16 v[20:23], v[170:173], v[232:235], v[20:23]
	v_mfma_f32_16x16x32_bf16 v[20:23], v[174:177], v[236:239], v[20:23]
	v_mfma_f32_16x16x32_bf16 v[12:15], v[198:201], v[236:239], v[12:15]
	v_mfma_f32_16x16x32_bf16 v[12:15], v[178:181], v[232:235], v[12:15]
	v_mfma_f32_16x16x32_bf16 v[8:11], v[170:173], v[240:243], v[8:11]
	v_mfma_f32_16x16x32_bf16 v[8:11], v[174:177], v[244:247], v[8:11]
	v_mfma_f32_16x16x32_bf16 v[4:7], v[198:201], v[244:247], v[4:7]
	v_mfma_f32_16x16x32_bf16 v[4:7], v[178:181], v[240:243], v[4:7]
	s_setprio 0
	s_barrier
	s_add_i32 s46, 0, 0x18000
	v_add_u32_e32 v2, s46, v168
	s_add_i32 s47, 0, 0x1c000
	ds_read_b128 v[132:135], v2
	ds_read_b128 v[136:139], v2 offset:1024
	ds_read_b128 v[140:143], v2 offset:2048
	ds_read_b128 v[144:147], v2 offset:3072
	v_add_u32_e32 v2, s47, v168
	ds_read_b128 v[170:173], v2
	ds_read_b128 v[174:177], v2 offset:1024
	ds_read_b128 v[178:181], v2 offset:2048
	ds_read_b128 v[198:201], v2 offset:3072
	s_add_u32 s18, s18, 0x80000
	s_addc_u32 s19, s19, 0
	s_mov_b32 m0, s27
	v_lshl_add_u64 v[186:187], s[18:19], 0, v[156:157]
	ds_read_b128 v[202:205], v169 offset:32768
	ds_read_b128 v[220:223], v169 offset:33792
	ds_read_b128 v[224:227], v169 offset:34816
	ds_read_b128 v[228:231], v169 offset:35840
	ds_read_b128 v[232:235], v169 offset:36864
	ds_read_b128 v[236:239], v169 offset:37888
	ds_read_b128 v[240:243], v169 offset:38912
	ds_read_b128 v[244:247], v169 offset:39936
	global_load_lds_dwordx4 v[186:187], off
	v_lshl_add_u64 v[186:187], s[18:19], 0, v[152:153]
	s_mov_b32 m0, s28
	s_nop 0
	global_load_lds_dwordx4 v[186:187], off
	s_waitcnt vmcnt(8)
	s_waitcnt lgkmcnt(0)
	s_barrier
	s_setprio 1
	s_waitcnt lgkmcnt(0)
	v_mfma_f32_16x16x32_bf16 v[128:131], v[132:135], v[202:205], v[128:131]
	v_mfma_f32_16x16x32_bf16 v[128:131], v[136:139], v[220:223], v[128:131]
	v_mfma_f32_16x16x32_bf16 v[124:127], v[144:147], v[220:223], v[124:127]
	v_mfma_f32_16x16x32_bf16 v[124:127], v[140:143], v[202:205], v[124:127]
	v_mfma_f32_16x16x32_bf16 v[120:123], v[132:135], v[224:227], v[120:123]
	v_mfma_f32_16x16x32_bf16 v[120:123], v[136:139], v[228:231], v[120:123]
	v_mfma_f32_16x16x32_bf16 v[112:115], v[144:147], v[228:231], v[112:115]
	v_mfma_f32_16x16x32_bf16 v[112:115], v[140:143], v[224:227], v[112:115]
	v_mfma_f32_16x16x32_bf16 v[104:107], v[132:135], v[232:235], v[104:107]
	v_mfma_f32_16x16x32_bf16 v[104:107], v[136:139], v[236:239], v[104:107]
	v_mfma_f32_16x16x32_bf16 v[96:99], v[144:147], v[236:239], v[96:99]
	v_mfma_f32_16x16x32_bf16 v[96:99], v[140:143], v[232:235], v[96:99]
	v_mfma_f32_16x16x32_bf16 v[88:91], v[132:135], v[240:243], v[88:91]
	v_mfma_f32_16x16x32_bf16 v[88:91], v[136:139], v[244:247], v[88:91]
	v_mfma_f32_16x16x32_bf16 v[80:83], v[144:147], v[244:247], v[80:83]
	v_mfma_f32_16x16x32_bf16 v[80:83], v[140:143], v[240:243], v[80:83]
	s_setprio 0
	s_setprio 1
	v_mfma_f32_16x16x32_bf16 v[116:119], v[170:173], v[202:205], v[116:119]
	v_mfma_f32_16x16x32_bf16 v[116:119], v[174:177], v[220:223], v[116:119]
	v_mfma_f32_16x16x32_bf16 v[108:111], v[198:201], v[220:223], v[108:111]
	v_mfma_f32_16x16x32_bf16 v[108:111], v[178:181], v[202:205], v[108:111]
	v_mfma_f32_16x16x32_bf16 v[100:103], v[170:173], v[224:227], v[100:103]
	v_mfma_f32_16x16x32_bf16 v[100:103], v[174:177], v[228:231], v[100:103]
	v_mfma_f32_16x16x32_bf16 v[92:95], v[198:201], v[228:231], v[92:95]
	v_mfma_f32_16x16x32_bf16 v[92:95], v[178:181], v[224:227], v[92:95]
	v_mfma_f32_16x16x32_bf16 v[84:87], v[170:173], v[232:235], v[84:87]
	v_mfma_f32_16x16x32_bf16 v[84:87], v[174:177], v[236:239], v[84:87]
	v_mfma_f32_16x16x32_bf16 v[76:79], v[198:201], v[236:239], v[76:79]
	v_mfma_f32_16x16x32_bf16 v[76:79], v[178:181], v[232:235], v[76:79]
	v_mfma_f32_16x16x32_bf16 v[72:75], v[170:173], v[240:243], v[72:75]
	v_mfma_f32_16x16x32_bf16 v[72:75], v[174:177], v[244:247], v[72:75]
	v_mfma_f32_16x16x32_bf16 v[68:71], v[198:201], v[244:247], v[68:71]
	v_mfma_f32_16x16x32_bf16 v[68:71], v[178:181], v[240:243], v[68:71]
	s_setprio 0
	s_barrier
; #define PG8_STAGE(bufoff, gbase, voff) do { _Pragma("unroll") for (int _i = 0; _i < 2; ++_i) \
;         __builtin_amdgcn_global_load_lds((const unsigned*)((const char*)(gbase) + (voff)[_i]), (PG8_LAS unsigned*)(lds + (bufoff) + ldsw + _i * 8192), 16, 0, 0); } while (0)
; #define PG8_LDA(dst, b, h) do { _Pragma("unroll") for (int m = 0; m < 4; ++m) _Pragma("unroll") for (int k = 0; k < 2; ++k) dst[m][k] = *(const PG8_LAS bf16x8*)(lds + PG8_SA(b, h) + aoff + m * 2048 + k * 1024); } while (0)
; #define PG8_MMA(ai, bj, At, Bt) do { __builtin_amdgcn_s_setprio(1); _Pragma("unroll") for (int m = 0; m < 4; ++m) _Pragma("unroll") for (int n = 0; n < 2; ++n) _Pragma("unroll") for (int k = 0; k < 2; ++k) \
;         acc[ai][bj][m][n] = __builtin_amdgcn_mfma_f32_16x16x32_bf16(Bt[n][k], At[m][k], acc[ai][bj][m][n], 0, 0, 0); __builtin_amdgcn_s_setprio(0); } while (0)
; #define PG8_WAIT_V(n) asm volatile("s_waitcnt vmcnt(" #n ")" ::: "memory")
; #define PG8_WAIT_L(n) asm volatile("s_waitcnt lgkmcnt(" #n ")" ::: "memory")
; #define PG8_BAR __builtin_amdgcn_s_barrier()
; #define PG8_SCHED __builtin_amdgcn_sched_barrier(0)
; template <class Epi, class Sched, bool ALIGN_EPI = false, bool SP2 = false>
; __device__ __forceinline__ void gemm_phase(PG8_LAS unsigned char* lds, const Gemm g, const Sched& S, const Epi& E) {
;     ...
;             PG8_WAIT_V(8); PG8_WAIT_L(0); PG8_BAR; PG8_MMA(0, 0, At, B0); PG8_MMA(0, 1, At, B1); PG8_BAR; PG8_SCHED;
;             PG8_LDA(At, 1, 1); PG8_STAGE(PG8_SB(1, 0), b3, voffB); PG8_STAGE(PG8_SB(1, 1), b3 + hstep, voffB); PG8_STAGE(PG8_SA(1, 0), a3, voffA);
;             PG8_WAIT_V(8); PG8_WAIT_L(0); PG8_BAR; PG8_MMA(1, 0, At, B0); PG8_MMA(1, 1, At, B1); PG8_BAR; PG8_SCHED;
	s_add_i32 s18, s46, s24
	v_lshl_add_u64 v[166:167], v[166:167], 0, s[34:35]
	s_mov_b32 m0, s18
	ds_read_b128 v[202:205], v169 offset:49152
	ds_read_b128 v[220:223], v169 offset:50176
	ds_read_b128 v[224:227], v169 offset:51200
	ds_read_b128 v[228:231], v169 offset:52224
	ds_read_b128 v[232:235], v169 offset:53248
	ds_read_b128 v[236:239], v169 offset:54272
	ds_read_b128 v[240:243], v169 offset:55296
	ds_read_b128 v[244:247], v169 offset:56320
	global_load_lds_dwordx4 v[166:167], off
	s_add_i32 m0, s18, 0x2000
	s_add_u32 s16, s16, 0x80080
	v_lshl_add_u64 v[166:167], v[196:197], 0, s[34:35]
	s_addc_u32 s17, s17, 0
	s_add_i32 s18, s47, s24
	global_load_lds_dwordx4 v[166:167], off
	v_lshl_add_u64 v[166:167], s[16:17], 0, v[154:155]
	s_mov_b32 m0, s18
	s_nop 0
	global_load_lds_dwordx4 v[166:167], off
	v_lshl_add_u64 v[166:167], s[16:17], 0, v[150:151]
	s_add_i32 m0, s18, 0x2000
	s_nop 0
	global_load_lds_dwordx4 v[166:167], off
	v_lshl_add_u64 v[166:167], v[206:207], 0, s[34:35]
	s_mov_b32 m0, s33
	s_nop 0
	global_load_lds_dwordx4 v[166:167], off
	v_lshl_add_u64 v[166:167], v[184:185], 0, s[34:35]
	s_mov_b32 m0, s38
	s_nop 0
	global_load_lds_dwordx4 v[166:167], off
	s_waitcnt vmcnt(8)
	s_waitcnt lgkmcnt(0)
	s_barrier
	s_setprio 1
	s_waitcnt lgkmcnt(0)
	v_mfma_f32_16x16x32_bf16 v[64:67], v[132:135], v[202:205], v[64:67]
	v_mfma_f32_16x16x32_bf16 v[64:67], v[136:139], v[220:223], v[64:67]
	v_mfma_f32_16x16x32_bf16 v[60:63], v[144:147], v[220:223], v[60:63]
	v_mfma_f32_16x16x32_bf16 v[60:63], v[140:143], v[202:205], v[60:63]
	v_mfma_f32_16x16x32_bf16 v[56:59], v[132:135], v[224:227], v[56:59]
	v_mfma_f32_16x16x32_bf16 v[56:59], v[136:139], v[228:231], v[56:59]
	v_mfma_f32_16x16x32_bf16 v[48:51], v[144:147], v[228:231], v[48:51]
	v_mfma_f32_16x16x32_bf16 v[48:51], v[140:143], v[224:227], v[48:51]
	v_mfma_f32_16x16x32_bf16 v[40:43], v[132:135], v[232:235], v[40:43]
	v_mfma_f32_16x16x32_bf16 v[40:43], v[136:139], v[236:239], v[40:43]
	v_mfma_f32_16x16x32_bf16 v[32:35], v[144:147], v[236:239], v[32:35]
	v_mfma_f32_16x16x32_bf16 v[32:35], v[140:143], v[232:235], v[32:35]
	v_mfma_f32_16x16x32_bf16 v[24:27], v[132:135], v[240:243], v[24:27]
	v_mfma_f32_16x16x32_bf16 v[24:27], v[136:139], v[244:247], v[24:27]
	v_mfma_f32_16x16x32_bf16 v[16:19], v[144:147], v[244:247], v[16:19]
	v_mfma_f32_16x16x32_bf16 v[16:19], v[140:143], v[240:243], v[16:19]
	s_setprio 0
	s_setprio 1
	v_mfma_f32_16x16x32_bf16 v[52:55], v[170:173], v[202:205], v[52:55]
	v_mfma_f32_16x16x32_bf16 v[52:55], v[174:177], v[220:223], v[52:55]
	v_mfma_f32_16x16x32_bf16 v[44:47], v[198:201], v[220:223], v[44:47]
	v_mfma_f32_16x16x32_bf16 v[44:47], v[178:181], v[202:205], v[44:47]
	v_mfma_f32_16x16x32_bf16 v[36:39], v[170:173], v[224:227], v[36:39]
	v_mfma_f32_16x16x32_bf16 v[36:39], v[174:177], v[228:231], v[36:39]
	v_mfma_f32_16x16x32_bf16 v[28:31], v[198:201], v[228:231], v[28:31]
	v_mfma_f32_16x16x32_bf16 v[28:31], v[178:181], v[224:227], v[28:31]
	v_mfma_f32_16x16x32_bf16 v[20:23], v[170:173], v[232:235], v[20:23]
	v_mfma_f32_16x16x32_bf16 v[20:23], v[174:177], v[236:239], v[20:23]
	v_mfma_f32_16x16x32_bf16 v[12:15], v[198:201], v[236:239], v[12:15]
	v_mfma_f32_16x16x32_bf16 v[12:15], v[178:181], v[232:235], v[12:15]
	v_mfma_f32_16x16x32_bf16 v[8:11], v[170:173], v[240:243], v[8:11]
	v_mfma_f32_16x16x32_bf16 v[8:11], v[174:177], v[244:247], v[8:11]
	v_mfma_f32_16x16x32_bf16 v[4:7], v[198:201], v[244:247], v[4:7]
	v_mfma_f32_16x16x32_bf16 v[4:7], v[178:181], v[240:243], v[4:7]
	s_setprio 0
	s_barrier
	s_add_i32 s45, s45, 2
	s_add_u32 s14, s14, 0x100
	s_addc_u32 s15, s15, 0
	s_add_u32 s43, s43, 0x100
	s_addc_u32 s44, s44, 0
	s_cmp_gt_u32 s45, 29
	s_cbranch_scc0 .LBB11_1071
	s_and_b64 vcc, exec, s[4:5]
	s_cbranch_vccz .LBB11_1074
	s_barrier

; #define PG8_STAGE(bufoff, gbase, voff) do { _Pragma("unroll") for (int _i = 0; _i < 2; ++_i) \
;         __builtin_amdgcn_global_load_lds((const unsigned*)((const char*)(gbase) + (voff)[_i]), (PG8_LAS unsigned*)(lds + (bufoff) + ldsw + _i * 8192), 16, 0, 0); } while (0)
; #define PG8_LDA(dst, b, h) do { _Pragma("unroll") for (int m = 0; m < 4; ++m) _Pragma("unroll") for (int k = 0; k < 2; ++k) dst[m][k] = *(const PG8_LAS bf16x8*)(lds + PG8_SA(b, h) + aoff + m * 2048 + k * 1024); } while (0)
; #define PG8_LDB(dst, b, h) do { _Pragma("unroll") for (int n = 0; n < 2; ++n) _Pragma("unroll") for (int k = 0; k < 2; ++k) dst[n][k] = *(const PG8_LAS bf16x8*)(lds + PG8_SB(b, h) + boff + n * 2048 + k * 1024); } while (0)
; template <class Epi, class Sched, bool ALIGN_EPI = false, bool SP2 = false>
; __device__ __forceinline__ void gemm_phase(PG8_LAS unsigned char* lds, const Gemm g, const Sched& S, const Epi& E) {
;     ...
;         for (int t = 0; t < nt; t += 2) {
;             const bool last = (t == nt - 2);
;             const char* a1 = cA + (size_t)(t + 1) * kstep;
;             const char* a2 = last ? nA : cA + (size_t)(t + 2) * kstep; const char* b2 = last ? nB : cB + (size_t)(t + 2) * kstep;
;             const char* a3 = a2 + kstep; const char* b3 = b2 + kstep;
;             if (last && has_next) S.a_ready(nxt);
;             if constexpr (SP2) {
;             PG8_LDB(B0, 0, 0); PG8_LDB(B1, 0, 1); PG8_SCHED; PG8_LDA(At, 0, 0); PG8_STAGE(PG8_SA(1, 1), a1 + hstep, voffA);
;             PG8_WAIT_V(8); PG8_WAIT_L(0); PG8_BAR; PG8_MMA(0, 0, At, B0); PG8_MMA(0, 1, At, B1); PG8_BAR; PG8_SCHED;
;             PG8_LDA(At, 0, 1); PG8_STAGE(PG8_SB(0, 0), b2, voffB); PG8_STAGE(PG8_SB(0, 1), b2 + hstep, voffB); PG8_STAGE(PG8_SA(0, 0), a2, voffA);
;             PG8_WAIT_V(8); PG8_WAIT_L(0); PG8_BAR; PG8_MMA(1, 0, At, B0); PG8_MMA(1, 1, At, B1); PG8_BAR; PG8_SCHED;
;             PG8_LDB(B0, 1, 0); PG8_LDB(B1, 1, 1); PG8_SCHED; PG8_LDA(At, 1, 0); PG8_STAGE(PG8_SA(0, 1), a2 + hstep, voffA);
;             PG8_WAIT_V(8); PG8_WAIT_L(0); PG8_BAR; PG8_MMA(0, 0, At, B0); PG8_MMA(0, 1, At, B1); PG8_BAR; PG8_SCHED;
;             PG8_LDA(At, 1, 1); PG8_STAGE(PG8_SB(1, 0), b3, voffB); PG8_STAGE(PG8_SB(1, 1), b3 + hstep, voffB); PG8_STAGE(PG8_SA(1, 0), a3, voffA);
;             PG8_WAIT_V(8); PG8_WAIT_L(0); PG8_BAR; PG8_MMA(1, 0, At, B0); PG8_MMA(1, 1, At, B1); PG8_BAR; PG8_SCHED;
.LBB11_1896:
	s_add_i32 s56, s22, 2
	s_add_u32 s57, s16, s20
	s_addc_u32 s23, s17, s21
	s_add_u32 s58, s14, s20
	s_addc_u32 s59, s15, s21
	s_add_i32 s60, 0, 0x10000
	s_cmp_eq_u32 s49, s22
	s_cselect_b32 s23, s5, s23
	s_cselect_b32 s22, s4, s57
	s_cselect_b32 s59, s19, s59
	s_cselect_b32 s58, s18, s58
	s_add_i32 s57, 0, 0x14000
	v_add_u32_e32 v156, s60, v1
	v_add_u32_e32 v174, s57, v1
	ds_read_b128 v[144:147], v156
	ds_read_b128 v[148:151], v156 offset:1024
	ds_read_b128 v[152:155], v156 offset:2048
	ds_read_b128 v[156:159], v156 offset:3072
	ds_read_b128 v[160:163], v174
	ds_read_b128 v[166:169], v174 offset:1024
	ds_read_b128 v[170:173], v174 offset:2048
	ds_read_b128 v[174:177], v174 offset:3072
	v_lshl_add_u64 v[184:185], s[16:17], 0, v[140:141]
	s_add_i32 m0, s45, 0xc000
	ds_read_b128 v[178:181], v143
	ds_read_b128 v[198:201], v143 offset:1024
	ds_read_b128 v[202:205], v143 offset:2048
	ds_read_b128 v[220:223], v143 offset:3072
	ds_read_b128 v[224:227], v143 offset:4096
	ds_read_b128 v[228:231], v143 offset:5120
	ds_read_b128 v[232:235], v143 offset:6144
	ds_read_b128 v[236:239], v143 offset:7168
	global_load_lds_dwordx4 v[184:185], off
	v_lshl_add_u64 v[184:185], s[16:17], 0, v[138:139]
	s_add_i32 m0, s45, 0xe000
	s_nop 0
	global_load_lds_dwordx4 v[184:185], off
	s_waitcnt vmcnt(8)
	s_waitcnt lgkmcnt(0)
	s_barrier
	s_setprio 1
	s_waitcnt lgkmcnt(0)
	v_mfma_f32_16x16x32_bf16 v[100:103], v[144:147], v[178:181], v[100:103]
	v_mfma_f32_16x16x32_bf16 v[100:103], v[148:151], v[198:201], v[100:103]
	v_mfma_f32_16x16x32_bf16 v[68:71], v[156:159], v[198:201], v[68:71]
	v_mfma_f32_16x16x32_bf16 v[68:71], v[152:155], v[178:181], v[68:71]
	v_mfma_f32_16x16x32_bf16 v[116:119], v[144:147], v[202:205], v[116:119]
	v_mfma_f32_16x16x32_bf16 v[116:119], v[148:151], v[220:223], v[116:119]
	v_mfma_f32_16x16x32_bf16 v[80:83], v[156:159], v[220:223], v[80:83]
	v_mfma_f32_16x16x32_bf16 v[80:83], v[152:155], v[202:205], v[80:83]
	v_mfma_f32_16x16x32_bf16 v[124:127], v[144:147], v[224:227], v[124:127]
	v_mfma_f32_16x16x32_bf16 v[124:127], v[148:151], v[228:231], v[124:127]
	v_mfma_f32_16x16x32_bf16 v[104:107], v[156:159], v[228:231], v[104:107]
	v_mfma_f32_16x16x32_bf16 v[104:107], v[152:155], v[224:227], v[104:107]
	v_mfma_f32_16x16x32_bf16 v[128:131], v[144:147], v[232:235], v[128:131]
	v_mfma_f32_16x16x32_bf16 v[128:131], v[148:151], v[236:239], v[128:131]
	v_mfma_f32_16x16x32_bf16 v[120:123], v[156:159], v[236:239], v[120:123]
	v_mfma_f32_16x16x32_bf16 v[120:123], v[152:155], v[232:235], v[120:123]
	s_setprio 0
	s_setprio 1
	v_mfma_f32_16x16x32_bf16 v[16:19], v[160:163], v[178:181], v[16:19]
	v_mfma_f32_16x16x32_bf16 v[16:19], v[166:169], v[198:201], v[16:19]
	v_mfma_f32_16x16x32_bf16 v[4:7], v[174:177], v[198:201], v[4:7]
	v_mfma_f32_16x16x32_bf16 v[4:7], v[170:173], v[178:181], v[4:7]
	v_mfma_f32_16x16x32_bf16 v[32:35], v[160:163], v[202:205], v[32:35]
	v_mfma_f32_16x16x32_bf16 v[32:35], v[166:169], v[220:223], v[32:35]
	v_mfma_f32_16x16x32_bf16 v[8:11], v[174:177], v[220:223], v[8:11]
	v_mfma_f32_16x16x32_bf16 v[8:11], v[170:173], v[202:205], v[8:11]
	v_mfma_f32_16x16x32_bf16 v[48:51], v[160:163], v[224:227], v[48:51]
	v_mfma_f32_16x16x32_bf16 v[48:51], v[166:169], v[228:231], v[48:51]
	v_mfma_f32_16x16x32_bf16 v[12:15], v[174:177], v[228:231], v[12:15]
	v_mfma_f32_16x16x32_bf16 v[12:15], v[170:173], v[224:227], v[12:15]
	v_mfma_f32_16x16x32_bf16 v[76:79], v[160:163], v[232:235], v[76:79]
	v_mfma_f32_16x16x32_bf16 v[76:79], v[166:169], v[236:239], v[76:79]
	v_mfma_f32_16x16x32_bf16 v[24:27], v[174:177], v[236:239], v[24:27]
	v_mfma_f32_16x16x32_bf16 v[24:27], v[170:173], v[232:235], v[24:27]
	s_setprio 0
	s_barrier
	s_add_i32 s60, s60, s13
	v_lshl_add_u64 v[184:185], s[58:59], 0, v[2:3]
	s_mov_b32 m0, s60
	ds_read_b128 v[178:181], v143 offset:16384
	ds_read_b128 v[198:201], v143 offset:17408
	ds_read_b128 v[202:205], v143 offset:18432
	ds_read_b128 v[220:223], v143 offset:19456
	ds_read_b128 v[224:227], v143 offset:20480
	ds_read_b128 v[228:231], v143 offset:21504
	ds_read_b128 v[232:235], v143 offset:22528
	ds_read_b128 v[236:239], v143 offset:23552
	global_load_lds_dwordx4 v[184:185], off
	s_add_i32 m0, s60, 0x2000
	v_lshl_add_u64 v[186:187], s[58:59], 0, v[132:133]
	s_add_u32 s58, s58, s33
	s_addc_u32 s59, s59, 0
	s_add_i32 s57, s57, s13
	global_load_lds_dwordx4 v[186:187], off
	v_lshl_add_u64 v[196:197], s[58:59], 0, v[2:3]
	s_mov_b32 m0, s57
	v_lshl_add_u64 v[206:207], s[58:59], 0, v[132:133]
	global_load_lds_dwordx4 v[196:197], off
	s_add_i32 m0, s57, 0x2000
	v_lshl_add_u64 v[240:241], s[22:23], 0, v[2:3]
	global_load_lds_dwordx4 v[206:207], off
	s_mov_b32 m0, s45
	v_lshl_add_u64 v[242:243], s[22:23], 0, v[132:133]
	global_load_lds_dwordx4 v[240:241], off
	s_mov_b32 m0, s46
	s_nop 0
	global_load_lds_dwordx4 v[242:243], off
	s_waitcnt vmcnt(8)
	s_waitcnt lgkmcnt(0)
	s_barrier
; #define PG8_STAGE(bufoff, gbase, voff) do { _Pragma("unroll") for (int _i = 0; _i < 2; ++_i) \
;         __builtin_amdgcn_global_load_lds((const unsigned*)((const char*)(gbase) + (voff)[_i]), (PG8_LAS unsigned*)(lds + (bufoff) + ldsw + _i * 8192), 16, 0, 0); } while (0)
; #define PG8_LDA(dst, b, h) do { _Pragma("unroll") for (int m = 0; m < 4; ++m) _Pragma("unroll") for (int k = 0; k < 2; ++k) dst[m][k] = *(const PG8_LAS bf16x8*)(lds + PG8_SA(b, h) + aoff + m * 2048 + k * 1024); } while (0)
; #define PG8_LDB(dst, b, h) do { _Pragma("unroll") for (int n = 0; n < 2; ++n) _Pragma("unroll") for (int k = 0; k < 2; ++k) dst[n][k] = *(const PG8_LAS bf16x8*)(lds + PG8_SB(b, h) + boff + n * 2048 + k * 1024); } while (0)
; #define PG8_MMA(ai, bj, At, Bt) do { __builtin_amdgcn_s_setprio(1); _Pragma("unroll") for (int m = 0; m < 4; ++m) _Pragma("unroll") for (int n = 0; n < 2; ++n) _Pragma("unroll") for (int k = 0; k < 2; ++k) \
;         acc[ai][bj][m][n] = __builtin_amdgcn_mfma_f32_16x16x32_bf16(Bt[n][k], At[m][k], acc[ai][bj][m][n], 0, 0, 0); __builtin_amdgcn_s_setprio(0); } while (0)
; #define PG8_WAIT_V(n) asm volatile("s_waitcnt vmcnt(" #n ")" ::: "memory")
; #define PG8_WAIT_L(n) asm volatile("s_waitcnt lgkmcnt(" #n ")" ::: "memory")
; #define PG8_BAR __builtin_amdgcn_s_barrier()
; #define PG8_SCHED __builtin_amdgcn_sched_barrier(0)
; template <class Epi, class Sched, bool ALIGN_EPI = false, bool SP2 = false>
; __device__ __forceinline__ void gemm_phase(PG8_LAS unsigned char* lds, const Gemm g, const Sched& S, const Epi& E) {
;     ...
;             PG8_LDB(B0, 0, 0); PG8_LDB(B1, 0, 1); PG8_SCHED; PG8_LDA(At, 0, 0); PG8_STAGE(PG8_SA(1, 1), a1 + hstep, voffA);
;             PG8_WAIT_V(8); PG8_WAIT_L(0); PG8_BAR; PG8_MMA(0, 0, At, B0); PG8_MMA(0, 1, At, B1); PG8_BAR; PG8_SCHED;
;             PG8_LDA(At, 0, 1); PG8_STAGE(PG8_SB(0, 0), b2, voffB); PG8_STAGE(PG8_SB(0, 1), b2 + hstep, voffB); PG8_STAGE(PG8_SA(0, 0), a2, voffA);
;             PG8_WAIT_V(8); PG8_WAIT_L(0); PG8_BAR; PG8_MMA(1, 0, At, B0); PG8_MMA(1, 1, At, B1); PG8_BAR; PG8_SCHED;
;             PG8_LDB(B0, 1, 0); PG8_LDB(B1, 1, 1); PG8_SCHED; PG8_LDA(At, 1, 0); PG8_STAGE(PG8_SA(0, 1), a2 + hstep, voffA);
;             PG8_WAIT_V(8); PG8_WAIT_L(0); PG8_BAR; PG8_MMA(0, 0, At, B0); PG8_MMA(0, 1, At, B1); PG8_BAR; PG8_SCHED;
	s_setprio 1
	s_waitcnt lgkmcnt(0)
	v_mfma_f32_16x16x32_bf16 v[108:111], v[144:147], v[178:181], v[108:111]
	v_mfma_f32_16x16x32_bf16 v[108:111], v[148:151], v[198:201], v[108:111]
	v_mfma_f32_16x16x32_bf16 v[112:115], v[156:159], v[198:201], v[112:115]
	v_mfma_f32_16x16x32_bf16 v[112:115], v[152:155], v[178:181], v[112:115]
	v_mfma_f32_16x16x32_bf16 v[88:91], v[144:147], v[202:205], v[88:91]
	v_mfma_f32_16x16x32_bf16 v[88:91], v[148:151], v[220:223], v[88:91]
	v_mfma_f32_16x16x32_bf16 v[92:95], v[156:159], v[220:223], v[92:95]
	v_mfma_f32_16x16x32_bf16 v[92:95], v[152:155], v[202:205], v[92:95]
	v_mfma_f32_16x16x32_bf16 v[60:63], v[144:147], v[224:227], v[60:63]
	v_mfma_f32_16x16x32_bf16 v[60:63], v[148:151], v[228:231], v[60:63]
	v_mfma_f32_16x16x32_bf16 v[64:67], v[156:159], v[228:231], v[64:67]
	v_mfma_f32_16x16x32_bf16 v[64:67], v[152:155], v[224:227], v[64:67]
	v_mfma_f32_16x16x32_bf16 v[36:39], v[144:147], v[232:235], v[36:39]
	v_mfma_f32_16x16x32_bf16 v[36:39], v[148:151], v[236:239], v[36:39]
	v_mfma_f32_16x16x32_bf16 v[40:43], v[156:159], v[236:239], v[40:43]
	v_mfma_f32_16x16x32_bf16 v[40:43], v[152:155], v[232:235], v[40:43]
	s_setprio 0
	s_setprio 1
	v_mfma_f32_16x16x32_bf16 v[96:99], v[160:163], v[178:181], v[96:99]
	v_mfma_f32_16x16x32_bf16 v[96:99], v[166:169], v[198:201], v[96:99]
	v_mfma_f32_16x16x32_bf16 v[44:47], v[174:177], v[198:201], v[44:47]
	v_mfma_f32_16x16x32_bf16 v[44:47], v[170:173], v[178:181], v[44:47]
	v_mfma_f32_16x16x32_bf16 v[84:87], v[160:163], v[202:205], v[84:87]
	v_mfma_f32_16x16x32_bf16 v[84:87], v[166:169], v[220:223], v[84:87]
	v_mfma_f32_16x16x32_bf16 v[72:75], v[174:177], v[220:223], v[72:75]
	v_mfma_f32_16x16x32_bf16 v[72:75], v[170:173], v[202:205], v[72:75]
	v_mfma_f32_16x16x32_bf16 v[56:59], v[160:163], v[224:227], v[56:59]
	v_mfma_f32_16x16x32_bf16 v[56:59], v[166:169], v[228:231], v[56:59]
	v_mfma_f32_16x16x32_bf16 v[52:55], v[174:177], v[228:231], v[52:55]
	v_mfma_f32_16x16x32_bf16 v[52:55], v[170:173], v[224:227], v[52:55]
	v_mfma_f32_16x16x32_bf16 v[28:31], v[160:163], v[232:235], v[28:31]
	v_mfma_f32_16x16x32_bf16 v[28:31], v[166:169], v[236:239], v[28:31]
	v_mfma_f32_16x16x32_bf16 v[20:23], v[174:177], v[236:239], v[20:23]
	v_mfma_f32_16x16x32_bf16 v[20:23], v[170:173], v[232:235], v[20:23]
	s_setprio 0
	s_barrier
	s_add_i32 s57, 0, 0x18000
	s_add_i32 s58, 0, 0x1c000
	v_add_u32_e32 v156, s57, v1
	v_add_u32_e32 v174, s58, v1
	ds_read_b128 v[144:147], v156
	ds_read_b128 v[148:151], v156 offset:1024
	ds_read_b128 v[152:155], v156 offset:2048
	ds_read_b128 v[156:159], v156 offset:3072
	ds_read_b128 v[160:163], v174
	ds_read_b128 v[166:169], v174 offset:1024
	ds_read_b128 v[170:173], v174 offset:2048
	ds_read_b128 v[174:177], v174 offset:3072
	s_add_u32 s22, s22, s33
	s_addc_u32 s23, s23, 0
	s_mov_b32 m0, s47
	v_lshl_add_u64 v[244:245], s[22:23], 0, v[2:3]
	ds_read_b128 v[178:181], v143 offset:32768
	ds_read_b128 v[198:201], v143 offset:33792
	ds_read_b128 v[202:205], v143 offset:34816
	ds_read_b128 v[220:223], v143 offset:35840
	ds_read_b128 v[224:227], v143 offset:36864
	ds_read_b128 v[228:231], v143 offset:37888
	ds_read_b128 v[232:235], v143 offset:38912
	ds_read_b128 v[236:239], v143 offset:39936
	global_load_lds_dwordx4 v[244:245], off
	v_lshl_add_u64 v[244:245], s[22:23], 0, v[132:133]
	s_mov_b32 m0, s48
	s_nop 0
	global_load_lds_dwordx4 v[244:245], off
	s_waitcnt vmcnt(8)
	s_waitcnt lgkmcnt(0)
	s_barrier
	s_setprio 1
	s_waitcnt lgkmcnt(0)
	v_mfma_f32_16x16x32_bf16 v[100:103], v[144:147], v[178:181], v[100:103]
	v_mfma_f32_16x16x32_bf16 v[100:103], v[148:151], v[198:201], v[100:103]
	v_mfma_f32_16x16x32_bf16 v[68:71], v[156:159], v[198:201], v[68:71]
	v_mfma_f32_16x16x32_bf16 v[68:71], v[152:155], v[178:181], v[68:71]
	v_mfma_f32_16x16x32_bf16 v[116:119], v[144:147], v[202:205], v[116:119]
	v_mfma_f32_16x16x32_bf16 v[116:119], v[148:151], v[220:223], v[116:119]
	v_mfma_f32_16x16x32_bf16 v[80:83], v[156:159], v[220:223], v[80:83]
	v_mfma_f32_16x16x32_bf16 v[80:83], v[152:155], v[202:205], v[80:83]
	v_mfma_f32_16x16x32_bf16 v[124:127], v[144:147], v[224:227], v[124:127]
	v_mfma_f32_16x16x32_bf16 v[124:127], v[148:151], v[228:231], v[124:127]
	v_mfma_f32_16x16x32_bf16 v[104:107], v[156:159], v[228:231], v[104:107]
	v_mfma_f32_16x16x32_bf16 v[104:107], v[152:155], v[224:227], v[104:107]
	v_mfma_f32_16x16x32_bf16 v[128:131], v[144:147], v[232:235], v[128:131]
	v_mfma_f32_16x16x32_bf16 v[128:131], v[148:151], v[236:239], v[128:131]
	v_mfma_f32_16x16x32_bf16 v[120:123], v[156:159], v[236:239], v[120:123]
	v_mfma_f32_16x16x32_bf16 v[120:123], v[152:155], v[232:235], v[120:123]
	s_setprio 0
	s_setprio 1
	v_mfma_f32_16x16x32_bf16 v[16:19], v[160:163], v[178:181], v[16:19]
	v_mfma_f32_16x16x32_bf16 v[16:19], v[166:169], v[198:201], v[16:19]
	v_mfma_f32_16x16x32_bf16 v[4:7], v[174:177], v[198:201], v[4:7]
	v_mfma_f32_16x16x32_bf16 v[4:7], v[170:173], v[178:181], v[4:7]
	v_mfma_f32_16x16x32_bf16 v[32:35], v[160:163], v[202:205], v[32:35]
	v_mfma_f32_16x16x32_bf16 v[32:35], v[166:169], v[220:223], v[32:35]
	v_mfma_f32_16x16x32_bf16 v[8:11], v[174:177], v[220:223], v[8:11]
	v_mfma_f32_16x16x32_bf16 v[8:11], v[170:173], v[202:205], v[8:11]
	v_mfma_f32_16x16x32_bf16 v[48:51], v[160:163], v[224:227], v[48:51]
	v_mfma_f32_16x16x32_bf16 v[48:51], v[166:169], v[228:231], v[48:51]
	v_mfma_f32_16x16x32_bf16 v[12:15], v[174:177], v[228:231], v[12:15]
	v_mfma_f32_16x16x32_bf16 v[12:15], v[170:173], v[224:227], v[12:15]
	v_mfma_f32_16x16x32_bf16 v[76:79], v[160:163], v[232:235], v[76:79]
	v_mfma_f32_16x16x32_bf16 v[76:79], v[166:169], v[236:239], v[76:79]
	v_mfma_f32_16x16x32_bf16 v[24:27], v[174:177], v[236:239], v[24:27]
	v_mfma_f32_16x16x32_bf16 v[24:27], v[170:173], v[232:235], v[24:27]
	s_setprio 0
	s_barrier
; template <class Epi, class Sched, bool ALIGN_EPI = false, bool SP2 = false>
; __device__ __forceinline__ void gemm_phase(PG8_LAS unsigned char* lds, const Gemm g, const Sched& S, const Epi& E) {
;     ...
;             PG8_WAIT_V(8); PG8_WAIT_L(0); PG8_BAR; PG8_MMA(0, 0, At, B0); PG8_MMA(0, 1, At, B1); PG8_BAR; PG8_SCHED;
;             PG8_LDA(At, 1, 1); PG8_STAGE(PG8_SB(1, 0), b3, voffB); PG8_STAGE(PG8_SB(1, 1), b3 + hstep, voffB); PG8_STAGE(PG8_SA(1, 0), a3, voffA);
;             PG8_WAIT_V(8); PG8_WAIT_L(0); PG8_BAR; PG8_MMA(1, 0, At, B0); PG8_MMA(1, 1, At, B1); PG8_BAR; PG8_SCHED;
;             } else {
;             PG8_LDB(B0, 0, 0); PG8_SCHED; PG8_LDA(At, 0, 0); PG8_STAGE(PG8_SA(1, 1), a1 + hstep, voffA);
;             PG8_WAIT_L(8); PG8_BAR; PG8_WAIT_L(0); PG8_MMA(0, 0, At, B0); PG8_BAR; PG8_SCHED;
;             PG8_LDB(B1, 0, 1); PG8_STAGE(PG8_SB(0, 0), b2, voffB);
;             PG8_BAR; PG8_WAIT_L(0); PG8_MMA(0, 1, At, B1); PG8_BAR;
;             PG8_LDA(At, 0, 1); PG8_STAGE(PG8_SA(0, 0), a2, voffA);
;             PG8_BAR; PG8_WAIT_L(0); PG8_MMA(1, 0, At, B0); PG8_BAR; PG8_SCHED;
;             PG8_STAGE(PG8_SB(0, 1), b2 + hstep, voffB);
;             PG8_WAIT_V(6); PG8_BAR; PG8_MMA(1, 1, At, B1); PG8_BAR;
;             PG8_LDB(B0, 1, 0); PG8_SCHED; PG8_LDA(At, 1, 0); PG8_STAGE(PG8_SA(0, 1), a2 + hstep, voffA);
;             PG8_WAIT_L(8); PG8_BAR; PG8_WAIT_L(0); PG8_MMA(0, 0, At, B0); PG8_BAR; PG8_SCHED;
;             PG8_LDB(B1, 1, 1); PG8_STAGE(PG8_SB(1, 0), b3, voffB);
;             PG8_BAR; PG8_WAIT_L(0); PG8_MMA(0, 1, At, B1); PG8_BAR;
;             PG8_LDA(At, 1, 1); PG8_STAGE(PG8_SA(1, 0), a3, voffA);
;             PG8_BAR; PG8_WAIT_L(0); PG8_MMA(1, 0, At, B0); PG8_BAR; PG8_SCHED;
;             PG8_STAGE(PG8_SB(1, 1), b3 + hstep, voffB);
;             PG8_WAIT_V(6); PG8_BAR; PG8_MMA(1, 1, At, B1); PG8_BAR;
;             }
;         }
;         if constexpr (ALIGN_EPI) { if (wr == 0) PG8_BAR; }
;         if constexpr (!Epi::AFTER_DRAIN) { E(acc, cur, wr, wc, fr, fq); S.done(cur); }
;         if (!has_next) break;
; #pragma unroll
;         for (int a = 0; a < 2; ++a)
; #pragma unroll
;             for (int b = 0; b < 2; ++b)
; #pragma unroll
;                 for (int m = 0; m < 4; ++m)
; #pragma unroll
;                     for (int n = 0; n < 2; ++n) acc[a][b][m][n] = (f32x4){0.f, 0.f, 0.f, 0.f};
;         cur = nxt; cA = nA; cB = nB; ++ui;
	s_add_i32 s22, s57, s13
	v_lshl_add_u64 v[184:185], v[184:185], 0, s[34:35]
	s_mov_b32 m0, s22
	ds_read_b128 v[178:181], v143 offset:49152
	ds_read_b128 v[198:201], v143 offset:50176
	ds_read_b128 v[202:205], v143 offset:51200
	ds_read_b128 v[220:223], v143 offset:52224
	ds_read_b128 v[224:227], v143 offset:53248
	ds_read_b128 v[228:231], v143 offset:54272
	ds_read_b128 v[232:235], v143 offset:55296
	ds_read_b128 v[236:239], v143 offset:56320
	global_load_lds_dwordx4 v[184:185], off
	v_lshl_add_u64 v[184:185], v[186:187], 0, s[34:35]
	s_add_i32 m0, s22, 0x2000
	s_add_i32 s22, s58, s13
	global_load_lds_dwordx4 v[184:185], off
	v_lshl_add_u64 v[184:185], v[196:197], 0, s[34:35]
	s_mov_b32 m0, s22
	s_nop 0
	global_load_lds_dwordx4 v[184:185], off
	v_lshl_add_u64 v[184:185], v[206:207], 0, s[34:35]
	s_add_i32 m0, s22, 0x2000
	s_nop 0
	global_load_lds_dwordx4 v[184:185], off
	v_lshl_add_u64 v[184:185], v[240:241], 0, s[34:35]
	s_mov_b32 m0, s50
	s_nop 0
	global_load_lds_dwordx4 v[184:185], off
	v_lshl_add_u64 v[184:185], v[242:243], 0, s[34:35]
	s_mov_b32 m0, s51
	s_nop 0
	global_load_lds_dwordx4 v[184:185], off
	s_waitcnt vmcnt(8)
	s_waitcnt lgkmcnt(0)
	s_barrier
	s_setprio 1
	s_waitcnt lgkmcnt(0)
	v_mfma_f32_16x16x32_bf16 v[108:111], v[144:147], v[178:181], v[108:111]
	v_mfma_f32_16x16x32_bf16 v[108:111], v[148:151], v[198:201], v[108:111]
	v_mfma_f32_16x16x32_bf16 v[112:115], v[156:159], v[198:201], v[112:115]
	v_mfma_f32_16x16x32_bf16 v[112:115], v[152:155], v[178:181], v[112:115]
	v_mfma_f32_16x16x32_bf16 v[88:91], v[144:147], v[202:205], v[88:91]
	v_mfma_f32_16x16x32_bf16 v[88:91], v[148:151], v[220:223], v[88:91]
	v_mfma_f32_16x16x32_bf16 v[92:95], v[156:159], v[220:223], v[92:95]
	v_mfma_f32_16x16x32_bf16 v[92:95], v[152:155], v[202:205], v[92:95]
	v_mfma_f32_16x16x32_bf16 v[60:63], v[144:147], v[224:227], v[60:63]
	v_mfma_f32_16x16x32_bf16 v[60:63], v[148:151], v[228:231], v[60:63]
	v_mfma_f32_16x16x32_bf16 v[64:67], v[156:159], v[228:231], v[64:67]
	v_mfma_f32_16x16x32_bf16 v[64:67], v[152:155], v[224:227], v[64:67]
	v_mfma_f32_16x16x32_bf16 v[36:39], v[144:147], v[232:235], v[36:39]
	v_mfma_f32_16x16x32_bf16 v[36:39], v[148:151], v[236:239], v[36:39]
	v_mfma_f32_16x16x32_bf16 v[40:43], v[156:159], v[236:239], v[40:43]
	v_mfma_f32_16x16x32_bf16 v[40:43], v[152:155], v[232:235], v[40:43]
	s_setprio 0
	s_setprio 1
	v_mfma_f32_16x16x32_bf16 v[96:99], v[160:163], v[178:181], v[96:99]
	v_mfma_f32_16x16x32_bf16 v[96:99], v[166:169], v[198:201], v[96:99]
	v_mfma_f32_16x16x32_bf16 v[44:47], v[174:177], v[198:201], v[44:47]
	v_mfma_f32_16x16x32_bf16 v[44:47], v[170:173], v[178:181], v[44:47]
	v_mfma_f32_16x16x32_bf16 v[84:87], v[160:163], v[202:205], v[84:87]
	v_mfma_f32_16x16x32_bf16 v[84:87], v[166:169], v[220:223], v[84:87]
	v_mfma_f32_16x16x32_bf16 v[72:75], v[174:177], v[220:223], v[72:75]
	v_mfma_f32_16x16x32_bf16 v[72:75], v[170:173], v[202:205], v[72:75]
	v_mfma_f32_16x16x32_bf16 v[56:59], v[160:163], v[224:227], v[56:59]
	v_mfma_f32_16x16x32_bf16 v[56:59], v[166:169], v[228:231], v[56:59]
	v_mfma_f32_16x16x32_bf16 v[52:55], v[174:177], v[228:231], v[52:55]
	v_mfma_f32_16x16x32_bf16 v[52:55], v[170:173], v[224:227], v[52:55]
	v_mfma_f32_16x16x32_bf16 v[28:31], v[160:163], v[232:235], v[28:31]
	v_mfma_f32_16x16x32_bf16 v[28:31], v[166:169], v[236:239], v[28:31]
	v_mfma_f32_16x16x32_bf16 v[20:23], v[174:177], v[236:239], v[20:23]
	v_mfma_f32_16x16x32_bf16 v[20:23], v[170:173], v[232:235], v[20:23]
	s_setprio 0
	s_barrier
	s_add_u32 s20, s20, 0x100
	s_addc_u32 s21, s21, 0
	v_lshl_add_u64 v[140:141], v[140:141], 0, s[62:63]
	v_lshl_add_u64 v[138:139], v[138:139], 0, s[62:63]
	s_cmp_ge_u32 s56, s29
	s_mov_b32 s22, s56
	s_cbranch_scc0 .LBB11_1896
	s_and_b64 vcc, exec, s[38:39]
	s_cbranch_vccnz .LBB11_1884
	v_mov_b32_e32 v20, 0
	s_mov_b32 s42, s53
	s_mov_b32 s28, s54
	s_mov_b64 s[14:15], s[18:19]
	s_mov_b64 s[16:17], s[4:5]
	s_mov_b32 s52, s55
	v_mov_b32_e32 v21, v20
	v_mov_b32_e32 v22, v20
	v_mov_b32_e32 v23, v20
	v_mov_b32_e32 v28, v20
	v_mov_b32_e32 v29, v20
	v_mov_b32_e32 v30, v20
	v_mov_b32_e32 v31, v20
	v_mov_b32_e32 v52, v20
	v_mov_b32_e32 v53, v20
	v_mov_b32_e32 v54, v20
	v_mov_b32_e32 v55, v20
	v_mov_b32_e32 v56, v20
	v_mov_b32_e32 v57, v20
	v_mov_b32_e32 v58, v20
	v_mov_b32_e32 v59, v20
	v_mov_b32_e32 v72, v20
	v_mov_b32_e32 v73, v20
	v_mov_b32_e32 v74, v20
	v_mov_b32_e32 v75, v20
	v_mov_b32_e32 v84, v20
	v_mov_b32_e32 v85, v20
	v_mov_b32_e32 v86, v20
	v_mov_b32_e32 v87, v20
	v_mov_b32_e32 v44, v20
	v_mov_b32_e32 v45, v20
	v_mov_b32_e32 v46, v20
	v_mov_b32_e32 v47, v20
	v_mov_b32_e32 v96, v20
	v_mov_b32_e32 v97, v20
	v_mov_b32_e32 v98, v20
	v_mov_b32_e32 v99, v20
	v_mov_b32_e32 v40, v20
	v_mov_b32_e32 v41, v20
	v_mov_b32_e32 v42, v20
	v_mov_b32_e32 v43, v20
	v_mov_b32_e32 v36, v20
	v_mov_b32_e32 v37, v20
	v_mov_b32_e32 v38, v20
	v_mov_b32_e32 v39, v20
	v_mov_b32_e32 v64, v20
	v_mov_b32_e32 v65, v20
	v_mov_b32_e32 v66, v20
	v_mov_b32_e32 v67, v20
	v_mov_b32_e32 v60, v20
	v_mov_b32_e32 v61, v20
	v_mov_b32_e32 v62, v20
	v_mov_b32_e32 v63, v20
	v_mov_b32_e32 v92, v20
	v_mov_b32_e32 v93, v20
	v_mov_b32_e32 v94, v20
	v_mov_b32_e32 v95, v20
	v_mov_b32_e32 v88, v20
	v_mov_b32_e32 v89, v20
	v_mov_b32_e32 v90, v20
	v_mov_b32_e32 v91, v20
	v_mov_b32_e32 v112, v20
	v_mov_b32_e32 v113, v20
	v_mov_b32_e32 v114, v20
	v_mov_b32_e32 v115, v20
	v_mov_b32_e32 v108, v20
	v_mov_b32_e32 v109, v20
	v_mov_b32_e32 v110, v20
	v_mov_b32_e32 v111, v20
	v_mov_b32_e32 v24, v20
	v_mov_b32_e32 v25, v20
	v_mov_b32_e32 v26, v20
	v_mov_b32_e32 v27, v20
	v_mov_b32_e32 v76, v20
	v_mov_b32_e32 v77, v20
	v_mov_b32_e32 v78, v20
	v_mov_b32_e32 v79, v20
	v_mov_b32_e32 v12, v20
	v_mov_b32_e32 v13, v20
	v_mov_b32_e32 v14, v20
	v_mov_b32_e32 v15, v20
	v_mov_b32_e32 v48, v20
	v_mov_b32_e32 v49, v20
	v_mov_b32_e32 v50, v20
	v_mov_b32_e32 v51, v20
	v_mov_b32_e32 v8, v20
	v_mov_b32_e32 v9, v20
	v_mov_b32_e32 v10, v20
	v_mov_b32_e32 v11, v20
	v_mov_b32_e32 v32, v20
	v_mov_b32_e32 v33, v20
	v_mov_b32_e32 v34, v20
	v_mov_b32_e32 v35, v20
	v_mov_b32_e32 v4, v20
	v_mov_b32_e32 v5, v20
	v_mov_b32_e32 v6, v20
	v_mov_b32_e32 v7, v20
	v_mov_b32_e32 v16, v20
	v_mov_b32_e32 v17, v20
	v_mov_b32_e32 v18, v20
	v_mov_b32_e32 v19, v20
	v_mov_b32_e32 v120, v20
	v_mov_b32_e32 v121, v20
	v_mov_b32_e32 v122, v20
	v_mov_b32_e32 v123, v20
	v_mov_b32_e32 v128, v20
	v_mov_b32_e32 v129, v20
	v_mov_b32_e32 v130, v20
	v_mov_b32_e32 v131, v20
	v_mov_b32_e32 v104, v20
	v_mov_b32_e32 v105, v20
	v_mov_b32_e32 v106, v20
	v_mov_b32_e32 v107, v20
	v_mov_b32_e32 v124, v20
	v_mov_b32_e32 v125, v20
	v_mov_b32_e32 v126, v20
	v_mov_b32_e32 v127, v20
	v_mov_b32_e32 v80, v20
	v_mov_b32_e32 v81, v20
	v_mov_b32_e32 v82, v20
	v_mov_b32_e32 v83, v20
	v_mov_b32_e32 v116, v20
	v_mov_b32_e32 v117, v20
	v_mov_b32_e32 v118, v20
	v_mov_b32_e32 v119, v20
	v_mov_b32_e32 v68, v20
	v_mov_b32_e32 v69, v20
	v_mov_b32_e32 v70, v20
	v_mov_b32_e32 v71, v20
	v_mov_b32_e32 v100, v20
	v_mov_b32_e32 v101, v20
	v_mov_b32_e32 v102, v20
	v_mov_b32_e32 v103, v20
	s_branch .LBB11_1884
